# t10 + 64B alignment of the streaming/unit loop heads (post-norm, transposes, mix, prep, NA/dil/GQA unit loops)
# baseline (speedup 1.0000x reference)
; __global__ void __launch_bounds__(512) mega(Args a) {
;     ...
;         for (int it = lyr * I_L + gwi; it < it_end; it += 2 * nwi) {
;           const bool h1 = it + nwi < it_end;
;           float v0[32], v1[32];
;           TR_DEC(it, T0) TR_DEC(h1 ? it + nwi : it, T1)
;           tr_load(T0, lane, v0); tr_load(T1, lane, v1);
;           tr_finish(T0, lane, v0, scr);
;           if (h1) tr_finish(T1, lane, v1, scr);
;         }
.LBB0_88:
	s_or_b64 exec, exec, s[0:1]
	v_add_u32_e32 v32, s17, v32
	s_waitcnt vmcnt(35)
	v_add_u32_e32 v3, s19, v32
	v_cmp_le_i32_e32 vcc, s16, v3
	s_or_b64 s[46:47], vcc, s[46:47]
	v_add_u32_e32 v1, s17, v1
	s_andn2_b64 exec, exec, s[46:47]
	s_cbranch_execz .LBB0_119
	.p2align	6

; __device__ __forceinline__ unsigned cvt_pk_bf16(float lo, float hi) { f32x2_t v = {lo, hi}; bf16x2_t r = __builtin_convertvector(v, bf16x2_t); return __builtin_bit_cast(unsigned, r); }
; __device__ __forceinline__ float bf_lo(unsigned w) { return __uint_as_float(w << 16); }
; __device__ __forceinline__ float bf_hi(unsigned w) { return __uint_as_float(w & 0xffff0000u); }
; __global__ void __launch_bounds__(512) mega(Args a) {
;     ...
;         const int hg = lane >> 4, e8 = (lane & 15) * 8;
;         struct MixIn { float l0, l1, l2; u32x4 o0, o1, o2, z; };
;         auto mix_load = [&](const int tok) { MixIn m;
;           m.l0 = LSE[((size_t)0 * MT + tok) * 4 + hg]; m.l1 = LSE[((size_t)1 * MT + tok) * 4 + hg]; m.l2 = LSE[((size_t)2 * MT + tok) * 4 + hg];
;           m.o0 = __builtin_nontemporal_load((const u32x4*)(OC + ((size_t)0 * MT + tok) * 512 + hg * 128 + e8)); m.o1 = __builtin_nontemporal_load((const u32x4*)(OC + ((size_t)1 * MT + tok) * 512 + hg * 128 + e8));
;           m.o2 = __builtin_nontemporal_load((const u32x4*)(OC + ((size_t)2 * MT + tok) * 512 + hg * 128 + e8)); m.z = *(const u32x4*)(PROJ + (size_t)tok * NIN + C_ZC + hg * 128 + e8); return m; };
;         auto mix_item = [&](const int tok, const MixIn& m) {
;           const float mx = fmaxf(m.l0, fmaxf(m.l1, m.l2)), e0 = __expf(m.l0 - mx), e1 = __expf(m.l1 - mx), e2 = __expf(m.l2 - mx), inv = 1.f / (e0 + e1 + e2);
;           const float w0 = e0 * inv, w1 = e1 * inv, w2 = e2 * inv;
;           u32x4 w;
; #pragma unroll
;           for (int q = 0; q < 4; ++q) { const float lo = (w0 * bf_lo(m.o0[q]) + w1 * bf_lo(m.o1[q]) + w2 * bf_lo(m.o2[q])) * bf_lo(m.z[q]), hi_ = (w0 * bf_hi(m.o0[q]) + w1 * bf_hi(m.o1[q]) + w2 * bf_hi(m.o2[q])) * bf_hi(m.z[q]); w[q] = cvt_pk_bf16(lo, hi_); }
;           *(u32x4*)(Y + (size_t)tok * YW + 2048 + hg * 128 + e8) = w; };
;         int tok0 = gw;
;         for (; tok0 + 3 * NGW < MT; tok0 += 4 * NGW) {
;           const MixIn m0 = mix_load(tok0), m1 = mix_load(tok0 + NGW), m2 = mix_load(tok0 + 2 * NGW), m3 = mix_load(tok0 + 3 * NGW);
.LBB0_188:
	v_mov_b32_e32 v177, v225
	s_mov_b32 s56, s78
	s_mov_b32 s57, s68
	s_lshl_b32 s10, s56, 3
	s_mov_b32 s28, s29
	s_add_u32 s0, s74, s28
	v_ashrrev_i32_e32 v0, 6, v177
	s_addc_u32 s1, s75, 0
	v_lshl_add_u32 v64, s57, 3, v0
	s_add_u32 s8, s0, 0x1a000000
	s_mul_i32 s2, s56, 24
	s_addc_u32 s9, s1, 0
	v_add_u32_e32 v0, s2, v64
	s_movk_i32 s3, 0x4000
	s_add_u32 s38, s0, 0x3d000000
	v_bfe_u32 v94, v177, 4, 2
	v_cmp_gt_i32_e32 vcc, s3, v0
	v_lshlrev_b32_e32 v0, 4, v177
	s_addc_u32 s39, s1, 0
	v_lshlrev_b32_e32 v66, 8, v94
	v_and_b32_e32 v95, 0xf0, v0
	s_and_saveexec_b64 s[30:31], vcc
	s_cbranch_execz .LBB0_192
	v_lshlrev_b32_e32 v0, 3, v177
	v_and_b32_e32 v0, 0x78, v0
	v_lshlrev_b32_e32 v192, 2, v94
	v_mov_b32_e32 v67, v193
	v_lshl_add_u64 v[2:3], s[0:1], 0, v[192:193]
	s_mov_b64 s[16:17], 0x48000000
	v_lshl_add_u64 v[4:5], s[0:1], 0, v[66:67]
	v_lshlrev_b32_e32 v6, 1, v0
	v_mov_b32_e32 v7, v193
	v_lshl_add_u64 v[68:69], v[2:3], 0, s[16:17]
	v_lshl_add_u64 v[4:5], v[4:5], 0, v[6:7]
	s_mov_b64 s[16:17], 0x45000000
	v_lshl_add_u64 v[70:71], v[4:5], 0, s[16:17]
	v_add_u32_e32 v4, s10, v64
	s_movk_i32 s15, 0x1400
	v_mad_i64_i32 v[6:7], s[16:17], v4, s15, 0
	v_readlane_b32 s20, v251, 0
	v_or3_b32 v6, v6, v66, v95
	v_readlane_b32 s21, v251, 1
	v_readlane_b32 s22, v251, 2
	v_ashrrev_i32_e32 v5, 31, v4
	v_lshl_add_u64 v[72:73], s[20:21], 0, v[6:7]
	v_mad_i64_i32 v[6:7], s[16:17], v4, s14, 0
	v_or3_b32 v6, v6, v66, v95
	v_readlane_b32 s23, v251, 3
	v_ashrrev_i32_e32 v65, 31, v64
	s_lshl_b32 s36, s56, 5
	v_lshl_add_u64 v[74:75], s[22:23], 0, v[6:7]
	v_lshlrev_b64 v[6:7], 10, v[4:5]
	v_lshlrev_b64 v[4:5], 4, v[4:5]
	v_or_b32_e32 v4, v4, v192
	v_lshl_add_u64 v[78:79], s[74:75], 0, v[4:5]
	v_mad_i64_i32 v[4:5], s[16:17], v64, s15, 0
	v_or3_b32 v4, v4, v66, v95
	v_lshl_add_u64 v[80:81], s[20:21], 0, v[4:5]
	v_mad_i64_i32 v[4:5], s[16:17], v64, s14, 0
	v_or3_b32 v4, v4, v66, v95
	v_lshl_add_u64 v[82:83], s[22:23], 0, v[4:5]
	v_lshlrev_b64 v[4:5], 10, v[64:65]
	v_or3_b32 v4, v4, v66, v95
	v_lshl_add_u64 v[84:85], s[74:75], 0, v[4:5]
	v_lshlrev_b64 v[4:5], 4, v[64:65]
	v_lshlrev_b32_e32 v2, 7, v94
	s_ashr_i32 s37, s36, 31
	v_or3_b32 v6, v6, v66, v95
	v_or_b32_e32 v4, v4, v192
	s_lshl_b32 s3, s56, 4
	s_mul_i32 s40, s56, 0x28000
	s_mul_hi_i32 s41, s36, 0x1400
	s_mul_i32 s42, s56, 0x118000
	s_mul_hi_i32 s43, s36, 0x8c00
	v_lshl_add_u64 v[76:77], s[74:75], 0, v[6:7]
	s_lshl_b64 s[44:45], s[36:37], 10
	s_lshl_b64 s[46:47], s[36:37], 4
	v_lshl_add_u64 v[86:87], s[74:75], 0, v[4:5]
	s_mov_b64 s[48:49], 0
	v_lshlrev_b32_e32 v192, 1, v2
	v_lshlrev_b32_e32 v88, 1, v0
	s_movk_i32 s19, 0x5000
	s_movk_i32 s20, 0x3fff
	s_mov_b64 s[22:23], 0x4000
	s_mov_b64 s[24:25], 0x8000
	.p2align	6

; __device__ __forceinline__ unsigned cvt_pk_bf16(float lo, float hi) { f32x2_t v = {lo, hi}; bf16x2_t r = __builtin_convertvector(v, bf16x2_t); return __builtin_bit_cast(unsigned, r); }
; __device__ __forceinline__ int crow(int r, int hi) { return (r & 3) + 8 * (r >> 2) + 4 * hi; }
; template <int MODE, int SDEPTH, bool SIMPLE>
; __device__ __forceinline__ void attn_body(const Unit& U, char* lds, const int tid) {
;     ...
;   if (hi == 0) li_l[r32] = l_reg; asm volatile("s_waitcnt lgkmcnt(0)" ::: "memory");
;   if constexpr (MODE == 2) { if (hi == 0) U.LSE[(long)(wid * QBLK + r32) * U.ldl] = m_reg * SCALE + __logf(l_reg); }
;   __syncthreads();
;   constexpr int OP = 136;
;   bf16_t* ol = (bf16_t*)lds + wid * (32 * OP);
; #pragma unroll
;   for (int r = 0; r < 16; ++r) { const float rl = __builtin_amdgcn_rcpf(li_l[crow(r, hi)]); bf16_t* op = ol + crow(r, hi) * OP + r32;
; #pragma unroll
;     for (int d0 = 0; d0 < 4; ++d0) op[d0 * 32] = (bf16_t)(cvt_pk_bf16(o[d0][r] * rl, 0.f) & 0xffffu); }
; __global__ void __launch_bounds__(512) mega(Args a) {
;     ...
;         const size_t tq = (size_t)b * SEQ + qb * 256;
;         U.Q = QBc + ((size_t)(b * 8 + h) * SEQ + qb * 256) * 128; U.K = KBc + (size_t)(b * 2 + (h >> 2)) * SEQ * 128; U.V = VBc + (size_t)(b * 2 + (h >> 2)) * SEQ * 128;
;         U.ldq = 128; U.ldk = 128; U.NT = SEQ / 64;
;         U.O = Y + tq * YW + 1024 + h * 128; U.ldo = YW; U.Z = PROJ + tq * NIN + C_ZB + h * 128; U.ldz = NIN;
.LBB0_197:
	s_or_b64 exec, exec, s[0:1]
	s_ashr_i32 s31, s30, 31
	s_lshl_b64 s[0:1], s[30:31], 13
	s_or_b32 s0, s0, s19
	s_mul_i32 s2, s1, 0x1400
	s_mul_hi_u32 s3, s0, 0x1400
	s_add_i32 s3, s3, s2
	s_mul_i32 s2, s0, 0x1400
	s_add_u32 s2, s38, s2
	s_mul_i32 s1, s1, 0x8c00
	s_mul_hi_u32 s15, s0, 0x8c00
	v_add_u32_e32 v65, v185, v192
	s_addc_u32 s3, s39, s3
	s_add_i32 s15, s15, s1
	s_mul_i32 s0, s0, 0x8c00
	s_waitcnt lgkmcnt(0)
	s_waitcnt lgkmcnt(0)
	s_barrier
	ds_read_b128 v[66:69], v65
	s_add_u32 s19, s8, s0
	s_addc_u32 s15, s9, s15
	s_lshl_b32 s16, s16, 8
	s_add_u32 s0, s2, s16
	s_addc_u32 s1, s3, 0
	s_add_u32 s2, s19, s16
	s_waitcnt lgkmcnt(0)
	v_rcp_f32_e32 v66, v66
	s_addc_u32 s3, s15, 0
	s_movk_i32 s15, 0x2200
	v_mul_lo_u32 v64, v184, s15
	v_add_u32_e32 v64, 0, v64
	v_lshl_add_u32 v70, v183, 1, v64
	s_movk_i32 s15, 0x440
	v_mul_f32_e32 v0, v0, v66
	v_mad_u32_u24 v71, v182, s15, v70
	v_cvt_pk_bf16_f32 v0, v0, s0
	ds_write_b16 v71, v0
	v_mul_f32_e32 v0, v48, v66
	v_cvt_pk_bf16_f32 v0, v0, s0
	ds_write_b16 v71, v0 offset:64
	v_mul_f32_e32 v0, v32, v66
	v_cvt_pk_bf16_f32 v0, v0, s0
	v_rcp_f32_e32 v32, v67
	ds_write_b16 v71, v0 offset:128
	v_mul_f32_e32 v0, v16, v66
	v_cvt_pk_bf16_f32 v0, v0, s0
	ds_write_b16 v71, v0 offset:192
	v_lshl_or_b32 v0, v182, 2, 1
	s_movk_i32 s15, 0x110
	v_mad_u32_u24 v16, v0, s15, v70
	v_mul_f32_e32 v0, v1, v32
	v_cvt_pk_bf16_f32 v0, v0, s0
	ds_write_b16 v16, v0
	v_mul_f32_e32 v0, v49, v32
	v_cvt_pk_bf16_f32 v0, v0, s0
	ds_write_b16 v16, v0 offset:64
	v_mul_f32_e32 v0, v33, v32
	v_cvt_pk_bf16_f32 v0, v0, s0
	ds_write_b16 v16, v0 offset:128
	v_mul_f32_e32 v0, v17, v32
	v_cvt_pk_bf16_f32 v0, v0, s0
	ds_write_b16 v16, v0 offset:192
	v_rcp_f32_e32 v0, v68
	v_lshlrev_b32_e32 v192, 1, v176
	s_add_i32 s62, s62, 1
	s_add_i32 s28, s28, s56
	v_mul_f32_e32 v1, v2, v0
	v_cvt_pk_bf16_f32 v1, v1, s0
	ds_write_b16 v16, v1 offset:272
	v_mul_f32_e32 v1, v50, v0
	v_cvt_pk_bf16_f32 v1, v1, s0
	ds_write_b16 v16, v1 offset:336
	v_mul_f32_e32 v1, v34, v0
	v_mul_f32_e32 v0, v18, v0
	v_cvt_pk_bf16_f32 v0, v0, s0
	ds_write_b16 v16, v0 offset:464
	v_rcp_f32_e32 v0, v69
	v_cvt_pk_bf16_f32 v1, v1, s0
	ds_write_b16 v16, v1 offset:400
	s_movk_i32 s69, 0x1400
	v_mul_f32_e32 v1, v3, v0
	v_cvt_pk_bf16_f32 v1, v1, s0
	ds_write_b16 v16, v1 offset:544
	v_mul_f32_e32 v1, v51, v0
	v_cvt_pk_bf16_f32 v1, v1, s0
	ds_write_b16 v16, v1 offset:608
	v_mul_f32_e32 v1, v35, v0
	v_mul_f32_e32 v0, v19, v0
	v_cvt_pk_bf16_f32 v1, v1, s0
	v_cvt_pk_bf16_f32 v0, v0, s0
	ds_write_b16 v16, v1 offset:672
	ds_write_b16 v16, v0 offset:736
	ds_read_b128 v[0:3], v65 offset:32
	s_waitcnt lgkmcnt(0)
	v_rcp_f32_e32 v0, v0
	s_nop 0
	v_mul_f32_e32 v4, v4, v0
	v_cvt_pk_bf16_f32 v4, v4, s0
	ds_write_b16 v16, v4 offset:1904
	v_mul_f32_e32 v4, v52, v0
	v_cvt_pk_bf16_f32 v4, v4, s0
	ds_write_b16 v16, v4 offset:1968
	v_mul_f32_e32 v4, v36, v0
	v_mul_f32_e32 v0, v20, v0
	v_cvt_pk_bf16_f32 v0, v0, s0
	ds_write_b16 v16, v0 offset:2096
	v_rcp_f32_e32 v0, v1
	v_cvt_pk_bf16_f32 v4, v4, s0
	ds_write_b16 v16, v4 offset:2032
	v_mul_f32_e32 v1, v5, v0
	v_cvt_pk_bf16_f32 v1, v1, s0
	ds_write_b16 v16, v1 offset:2176
	v_mul_f32_e32 v1, v53, v0
	v_cvt_pk_bf16_f32 v1, v1, s0
	ds_write_b16 v16, v1 offset:2240
	v_mul_f32_e32 v1, v37, v0
	v_mul_f32_e32 v0, v21, v0
	v_cvt_pk_bf16_f32 v0, v0, s0
	ds_write_b16 v16, v0 offset:2368
	v_rcp_f32_e32 v0, v2
	v_cvt_pk_bf16_f32 v1, v1, s0
	ds_write_b16 v16, v1 offset:2304
	v_mul_f32_e32 v1, v6, v0
	v_cvt_pk_bf16_f32 v1, v1, s0
	ds_write_b16 v16, v1 offset:2448
	v_mul_f32_e32 v1, v54, v0
	v_cvt_pk_bf16_f32 v1, v1, s0
	ds_write_b16 v16, v1 offset:2512
	v_mul_f32_e32 v1, v38, v0
	v_mul_f32_e32 v0, v22, v0
	v_cvt_pk_bf16_f32 v0, v0, s0
	ds_write_b16 v16, v0 offset:2640
	v_rcp_f32_e32 v0, v3
	v_cvt_pk_bf16_f32 v1, v1, s0
	ds_write_b16 v16, v1 offset:2576
	v_mul_f32_e32 v1, v7, v0
	v_cvt_pk_bf16_f32 v1, v1, s0
	ds_write_b16 v16, v1 offset:2720
	v_mul_f32_e32 v1, v55, v0
	v_cvt_pk_bf16_f32 v1, v1, s0
	ds_write_b16 v16, v1 offset:2784
	v_mul_f32_e32 v1, v39, v0
	v_mul_f32_e32 v0, v23, v0
	v_cvt_pk_bf16_f32 v1, v1, s0
	v_cvt_pk_bf16_f32 v0, v0, s0
	ds_write_b16 v16, v1 offset:2848
	ds_write_b16 v16, v0 offset:2912
	ds_read_b128 v[0:3], v65 offset:64
	s_waitcnt lgkmcnt(0)
	v_rcp_f32_e32 v0, v0
	s_nop 0
	v_mul_f32_e32 v4, v8, v0
	v_cvt_pk_bf16_f32 v4, v4, s0
	ds_write_b16 v16, v4 offset:4080
	v_mul_f32_e32 v4, v56, v0
	v_cvt_pk_bf16_f32 v4, v4, s0
	ds_write_b16 v16, v4 offset:4144
	v_mul_f32_e32 v4, v40, v0
	v_mul_f32_e32 v0, v24, v0
	v_cvt_pk_bf16_f32 v0, v0, s0
	ds_write_b16 v16, v0 offset:4272
	v_rcp_f32_e32 v0, v1
	v_cvt_pk_bf16_f32 v4, v4, s0
	ds_write_b16 v16, v4 offset:4208
	v_mul_f32_e32 v1, v9, v0
	v_cvt_pk_bf16_f32 v1, v1, s0
	ds_write_b16 v16, v1 offset:4352
	v_mul_f32_e32 v1, v57, v0
	v_cvt_pk_bf16_f32 v1, v1, s0
	ds_write_b16 v16, v1 offset:4416
	v_mul_f32_e32 v1, v41, v0
	v_mul_f32_e32 v0, v25, v0
	v_cvt_pk_bf16_f32 v0, v0, s0
	ds_write_b16 v16, v0 offset:4544
	v_rcp_f32_e32 v0, v2
	v_cvt_pk_bf16_f32 v1, v1, s0
	ds_write_b16 v16, v1 offset:4480
	v_mul_f32_e32 v1, v10, v0
	v_cvt_pk_bf16_f32 v1, v1, s0
	ds_write_b16 v16, v1 offset:4624
	v_mul_f32_e32 v1, v58, v0
	v_cvt_pk_bf16_f32 v1, v1, s0
	ds_write_b16 v16, v1 offset:4688
	v_mul_f32_e32 v1, v42, v0
	v_mul_f32_e32 v0, v26, v0
	v_cvt_pk_bf16_f32 v0, v0, s0
	ds_write_b16 v16, v0 offset:4816
	v_rcp_f32_e32 v0, v3
	v_cvt_pk_bf16_f32 v1, v1, s0
	ds_write_b16 v16, v1 offset:4752
	v_mul_f32_e32 v1, v11, v0
	v_cvt_pk_bf16_f32 v1, v1, s0
	ds_write_b16 v16, v1 offset:4896
	v_mul_f32_e32 v1, v59, v0
	v_cvt_pk_bf16_f32 v1, v1, s0
	ds_write_b16 v16, v1 offset:4960
	v_mul_f32_e32 v1, v43, v0
	v_mul_f32_e32 v0, v27, v0
	v_cvt_pk_bf16_f32 v1, v1, s0
	v_cvt_pk_bf16_f32 v0, v0, s0
	ds_write_b16 v16, v1 offset:5024
	ds_write_b16 v16, v0 offset:5088
	ds_read_b128 v[0:3], v65 offset:96
	s_waitcnt lgkmcnt(0)
; __device__ __forceinline__ unsigned cvt_pk_bf16(float lo, float hi) { f32x2_t v = {lo, hi}; bf16x2_t r = __builtin_convertvector(v, bf16x2_t); return __builtin_bit_cast(unsigned, r); }
; __device__ __forceinline__ float bf_lo(unsigned w) { return __uint_as_float(w << 16); }
; __device__ __forceinline__ float bf_hi(unsigned w) { return __uint_as_float(w & 0xffff0000u); }
; __device__ __forceinline__ int crow(int r, int hi) { return (r & 3) + 8 * (r >> 2) + 4 * hi; }
; template <int MODE, int SDEPTH, bool SIMPLE>
; __device__ __forceinline__ void attn_body(const Unit& U, char* lds, const int tid) {
;     ...
;   for (int r = 0; r < 16; ++r) { const float rl = __builtin_amdgcn_rcpf(li_l[crow(r, hi)]); bf16_t* op = ol + crow(r, hi) * OP + r32;
; #pragma unroll
;     for (int d0 = 0; d0 < 4; ++d0) op[d0 * 32] = (bf16_t)(cvt_pk_bf16(o[d0][r] * rl, 0.f) & 0xffffu); }
;   asm volatile("s_waitcnt lgkmcnt(0)" ::: "memory");
;   { const int cc = (lane & 15) * 8, rb = lane >> 4;
;     u32x4 zz[8];
;     if constexpr (MODE != 2) {
; #pragma unroll
;       for (int i = 0; i < 8; ++i) zz[i] = *(const u32x4*)(U.Z + (long)(wid * QBLK + rb + 4 * i) * U.ldz + cc);
;     }
; #pragma unroll
;     for (int i = 0; i < 8; ++i) { const int row = rb + 4 * i; const long orow = wid * QBLK + row;
;       u32x4 v = *(const u32x4*)(ol + row * OP + cc);
;       if constexpr (MODE != 2) { const u32x4 z = zz[i];
; #pragma unroll
;         for (int q = 0; q < 4; ++q) v[q] = cvt_pk_bf16(bf_lo(v[q]) * bf_lo(z[q]), bf_hi(v[q]) * bf_hi(z[q])); }
;       *(u32x4*)(U.O + orow * U.ldo + cc) = v; } }
	v_rcp_f32_e32 v0, v0
	s_nop 0
	v_mul_f32_e32 v4, v12, v0
	v_cvt_pk_bf16_f32 v4, v4, s0
	ds_write_b16 v16, v4 offset:6256
	v_mul_f32_e32 v4, v60, v0
	v_cvt_pk_bf16_f32 v4, v4, s0
	ds_write_b16 v16, v4 offset:6320
	v_mul_f32_e32 v4, v44, v0
	v_mul_f32_e32 v0, v28, v0
	v_cvt_pk_bf16_f32 v0, v0, s0
	ds_write_b16 v16, v0 offset:6448
	v_rcp_f32_e32 v0, v1
	v_cvt_pk_bf16_f32 v4, v4, s0
	v_lshrrev_b32_e32 v28, 4, v181
	ds_write_b16 v16, v4 offset:6384
	v_mul_f32_e32 v1, v13, v0
	v_cvt_pk_bf16_f32 v1, v1, s0
	ds_write_b16 v16, v1 offset:6528
	v_mul_f32_e32 v1, v61, v0
	v_cvt_pk_bf16_f32 v1, v1, s0
	ds_write_b16 v16, v1 offset:6592
	v_mul_f32_e32 v1, v45, v0
	v_mul_f32_e32 v0, v29, v0
	v_cvt_pk_bf16_f32 v0, v0, s0
	ds_write_b16 v16, v0 offset:6720
	v_rcp_f32_e32 v0, v2
	v_cvt_pk_bf16_f32 v1, v1, s0
	ds_write_b16 v16, v1 offset:6656
	v_mul_f32_e32 v1, v14, v0
	v_cvt_pk_bf16_f32 v1, v1, s0
	ds_write_b16 v16, v1 offset:6800
	v_mul_f32_e32 v1, v62, v0
	v_cvt_pk_bf16_f32 v1, v1, s0
	ds_write_b16 v16, v1 offset:6864
	v_mul_f32_e32 v1, v46, v0
	v_mul_f32_e32 v0, v30, v0
	v_cvt_pk_bf16_f32 v0, v0, s0
	ds_write_b16 v16, v0 offset:6992
	v_rcp_f32_e32 v0, v3
	v_cvt_pk_bf16_f32 v1, v1, s0
	ds_write_b16 v16, v1 offset:6928
	v_or_b32_e32 v46, v28, v180
	v_mul_f32_e32 v1, v15, v0
	v_cvt_pk_bf16_f32 v1, v1, s0
	ds_write_b16 v16, v1 offset:7072
	v_mul_f32_e32 v1, v63, v0
	v_cvt_pk_bf16_f32 v1, v1, s0
	ds_write_b16 v16, v1 offset:7136
	v_mul_f32_e32 v1, v47, v0
	v_mul_f32_e32 v0, v31, v0
	v_cvt_pk_bf16_f32 v1, v1, s0
	v_cvt_pk_bf16_f32 v0, v0, s0
	ds_write_b16 v16, v1 offset:7200
	ds_write_b16 v16, v0 offset:7264
	v_lshl_add_u64 v[0:1], s[2:3], 0, v[192:193]
	s_mov_b64 s[2:3], 0x5000
	v_lshl_add_u64 v[0:1], v[0:1], 0, s[2:3]
	s_waitcnt lgkmcnt(0)
	v_mad_i64_i32 v[2:3], s[2:3], v46, s14, v[0:1]
	global_load_dwordx4 v[36:39], v[2:3], off
	v_or_b32_e32 v47, 4, v46
	v_mad_i64_i32 v[2:3], s[2:3], v47, s14, v[0:1]
	global_load_dwordx4 v[24:27], v[2:3], off
	v_or_b32_e32 v48, 8, v46
	v_mad_i64_i32 v[2:3], s[2:3], v48, s14, v[0:1]
	global_load_dwordx4 v[20:23], v[2:3], off
	v_or_b32_e32 v35, 12, v46
	v_mad_i64_i32 v[2:3], s[2:3], v35, s14, v[0:1]
	global_load_dwordx4 v[16:19], v[2:3], off
	v_or_b32_e32 v34, 16, v46
	v_mad_i64_i32 v[2:3], s[2:3], v34, s14, v[0:1]
	global_load_dwordx4 v[12:15], v[2:3], off
	v_mul_u32_u24_e32 v28, 0x110, v28
	v_or_b32_e32 v33, 20, v46
	v_add3_u32 v31, v64, v192, v28
	v_mad_i64_i32 v[2:3], s[2:3], v33, s14, v[0:1]
	ds_read_b128 v[40:43], v31
	global_load_dwordx4 v[8:11], v[2:3], off
	v_or_b32_e32 v32, 24, v46
	v_or_b32_e32 v30, 28, v46
	v_mad_i64_i32 v[2:3], s[2:3], v32, s14, v[0:1]
	s_waitcnt lgkmcnt(0)
	v_lshlrev_b32_e32 v28, 16, v40
	v_and_b32_e32 v29, 0xffff0000, v40
	v_mad_i64_i32 v[0:1], s[2:3], v30, s14, v[0:1]
	s_movk_i32 s2, 0x1400
	global_load_dwordx4 v[4:7], v[2:3], off
	s_waitcnt vmcnt(6)
	v_lshlrev_b32_e32 v44, 16, v36
	v_and_b32_e32 v45, 0xffff0000, v36
	v_pk_mul_f32 v[28:29], v[44:45], v[28:29]
	v_lshlrev_b32_e32 v40, 16, v37
	v_cvt_pk_bf16_f32 v36, v28, v29
	v_lshlrev_b32_e32 v28, 16, v41
	v_and_b32_e32 v29, 0xffff0000, v41
	v_and_b32_e32 v41, 0xffff0000, v37
	v_pk_mul_f32 v[28:29], v[40:41], v[28:29]
	v_lshlrev_b32_e32 v40, 16, v38
	v_cvt_pk_bf16_f32 v37, v28, v29
	v_lshlrev_b32_e32 v28, 16, v42
	v_and_b32_e32 v29, 0xffff0000, v42
	v_and_b32_e32 v41, 0xffff0000, v38
	v_pk_mul_f32 v[28:29], v[40:41], v[28:29]
	v_lshlrev_b32_e32 v40, 16, v39
	v_cvt_pk_bf16_f32 v38, v28, v29
	v_lshlrev_b32_e32 v28, 16, v43
	v_and_b32_e32 v29, 0xffff0000, v43
	v_and_b32_e32 v41, 0xffff0000, v39
	v_pk_mul_f32 v[28:29], v[40:41], v[28:29]
	global_load_dwordx4 v[0:3], v[0:1], off
	v_cvt_pk_bf16_f32 v39, v28, v29
	v_mov_b64_e32 v[28:29], s[0:1]
	v_mad_i64_i32 v[40:41], s[0:1], v46, s2, v[28:29]
	v_lshl_add_u64 v[40:41], v[40:41], 0, v[192:193]
	global_store_dwordx4 v[40:41], v[36:39], off offset:2048 sc1
	ds_read_b128 v[36:39], v31 offset:1088
	s_waitcnt vmcnt(7)
	v_lshlrev_b32_e32 v42, 16, v24
	v_and_b32_e32 v43, 0xffff0000, v24
	s_waitcnt lgkmcnt(0)
	v_lshlrev_b32_e32 v40, 16, v36
	v_and_b32_e32 v41, 0xffff0000, v36
	v_pk_mul_f32 v[40:41], v[42:43], v[40:41]
	v_lshlrev_b32_e32 v36, 16, v37
	v_cvt_pk_bf16_f32 v24, v40, v41
	v_and_b32_e32 v37, 0xffff0000, v37
	v_lshlrev_b32_e32 v40, 16, v25
	v_and_b32_e32 v41, 0xffff0000, v25
	v_pk_mul_f32 v[36:37], v[40:41], v[36:37]
	v_lshlrev_b32_e32 v40, 16, v26
	v_cvt_pk_bf16_f32 v25, v36, v37
	v_lshlrev_b32_e32 v36, 16, v38
	v_and_b32_e32 v37, 0xffff0000, v38
	v_and_b32_e32 v41, 0xffff0000, v26
	v_pk_mul_f32 v[36:37], v[40:41], v[36:37]
	v_lshlrev_b32_e32 v38, 16, v27
	v_cvt_pk_bf16_f32 v26, v36, v37
	v_lshlrev_b32_e32 v36, 16, v39
	v_and_b32_e32 v37, 0xffff0000, v39
	v_and_b32_e32 v39, 0xffff0000, v27
	v_pk_mul_f32 v[36:37], v[38:39], v[36:37]
	s_waitcnt vmcnt(6)
	v_lshlrev_b32_e32 v38, 16, v20
	v_cvt_pk_bf16_f32 v27, v36, v37
	v_mad_i64_i32 v[36:37], s[0:1], v47, s2, v[28:29]
	v_lshl_add_u64 v[36:37], v[36:37], 0, v[192:193]
	global_store_dwordx4 v[36:37], v[24:27], off offset:2048 sc1
	ds_read_b128 v[24:27], v31 offset:2176
	v_and_b32_e32 v39, 0xffff0000, v20
	s_waitcnt lgkmcnt(0)
	v_lshlrev_b32_e32 v36, 16, v24
	v_and_b32_e32 v37, 0xffff0000, v24
	v_pk_mul_f32 v[36:37], v[38:39], v[36:37]
	v_lshlrev_b32_e32 v24, 16, v25
	v_cvt_pk_bf16_f32 v20, v36, v37
	v_and_b32_e32 v25, 0xffff0000, v25
	v_lshlrev_b32_e32 v36, 16, v21
	v_and_b32_e32 v37, 0xffff0000, v21
	v_pk_mul_f32 v[24:25], v[36:37], v[24:25]
	v_lshlrev_b32_e32 v36, 16, v22
	v_cvt_pk_bf16_f32 v21, v24, v25
	v_lshlrev_b32_e32 v24, 16, v26
	v_and_b32_e32 v25, 0xffff0000, v26
	v_and_b32_e32 v37, 0xffff0000, v22
	v_pk_mul_f32 v[24:25], v[36:37], v[24:25]
	v_lshlrev_b32_e32 v26, 16, v23
	v_cvt_pk_bf16_f32 v22, v24, v25
	v_lshlrev_b32_e32 v24, 16, v27
	v_and_b32_e32 v25, 0xffff0000, v27
	v_and_b32_e32 v27, 0xffff0000, v23
	v_pk_mul_f32 v[24:25], v[26:27], v[24:25]
	s_waitcnt vmcnt(6)
; __device__ __forceinline__ unsigned cvt_pk_bf16(float lo, float hi) { f32x2_t v = {lo, hi}; bf16x2_t r = __builtin_convertvector(v, bf16x2_t); return __builtin_bit_cast(unsigned, r); }
; __device__ __forceinline__ float bf_lo(unsigned w) { return __uint_as_float(w << 16); }
; __device__ __forceinline__ float bf_hi(unsigned w) { return __uint_as_float(w & 0xffff0000u); }
; template <int MODE, int SDEPTH, bool SIMPLE>
; __device__ __forceinline__ void attn_body(const Unit& U, char* lds, const int tid) {
;     ...
;       for (int i = 0; i < 8; ++i) zz[i] = *(const u32x4*)(U.Z + (long)(wid * QBLK + rb + 4 * i) * U.ldz + cc);
;     }
; #pragma unroll
;     for (int i = 0; i < 8; ++i) { const int row = rb + 4 * i; const long orow = wid * QBLK + row;
;       u32x4 v = *(const u32x4*)(ol + row * OP + cc);
;       if constexpr (MODE != 2) { const u32x4 z = zz[i];
; #pragma unroll
;         for (int q = 0; q < 4; ++q) v[q] = cvt_pk_bf16(bf_lo(v[q]) * bf_lo(z[q]), bf_hi(v[q]) * bf_hi(z[q])); }
;       *(u32x4*)(U.O + orow * U.ldo + cc) = v; } }
; __global__ void __launch_bounds__(512) mega(Args a) {
;     ...
;       for (int i = 0;; ++i) {
;         const int un = i * G + cu; if (un >= NB * 8 * 32) break;
	v_lshlrev_b32_e32 v26, 16, v16
	v_cvt_pk_bf16_f32 v23, v24, v25
	v_mad_i64_i32 v[24:25], s[0:1], v48, s2, v[28:29]
	v_lshl_add_u64 v[24:25], v[24:25], 0, v[192:193]
	global_store_dwordx4 v[24:25], v[20:23], off offset:2048 sc1
	ds_read_b128 v[20:23], v31 offset:3264
	v_and_b32_e32 v27, 0xffff0000, v16
	s_waitcnt lgkmcnt(0)
	v_lshlrev_b32_e32 v24, 16, v20
	v_and_b32_e32 v25, 0xffff0000, v20
	v_pk_mul_f32 v[24:25], v[26:27], v[24:25]
	v_lshlrev_b32_e32 v20, 16, v21
	v_cvt_pk_bf16_f32 v16, v24, v25
	v_and_b32_e32 v21, 0xffff0000, v21
	v_lshlrev_b32_e32 v24, 16, v17
	v_and_b32_e32 v25, 0xffff0000, v17
	v_pk_mul_f32 v[20:21], v[24:25], v[20:21]
	v_lshlrev_b32_e32 v24, 16, v18
	v_cvt_pk_bf16_f32 v17, v20, v21
	v_lshlrev_b32_e32 v20, 16, v22
	v_and_b32_e32 v21, 0xffff0000, v22
	v_and_b32_e32 v25, 0xffff0000, v18
	v_pk_mul_f32 v[20:21], v[24:25], v[20:21]
	v_lshlrev_b32_e32 v22, 16, v19
	v_cvt_pk_bf16_f32 v18, v20, v21
	v_lshlrev_b32_e32 v20, 16, v23
	v_and_b32_e32 v21, 0xffff0000, v23
	v_and_b32_e32 v23, 0xffff0000, v19
	v_pk_mul_f32 v[20:21], v[22:23], v[20:21]
	s_waitcnt vmcnt(6)
	v_lshlrev_b32_e32 v22, 16, v12
	v_cvt_pk_bf16_f32 v19, v20, v21
	v_mad_i64_i32 v[20:21], s[0:1], v35, s2, v[28:29]
	v_lshl_add_u64 v[20:21], v[20:21], 0, v[192:193]
	global_store_dwordx4 v[20:21], v[16:19], off offset:2048 sc1
	ds_read_b128 v[16:19], v31 offset:4352
	v_and_b32_e32 v23, 0xffff0000, v12
	s_waitcnt lgkmcnt(0)
	v_lshlrev_b32_e32 v20, 16, v16
	v_and_b32_e32 v21, 0xffff0000, v16
	v_pk_mul_f32 v[20:21], v[22:23], v[20:21]
	v_lshlrev_b32_e32 v16, 16, v17
	v_cvt_pk_bf16_f32 v12, v20, v21
	v_and_b32_e32 v17, 0xffff0000, v17
	v_lshlrev_b32_e32 v20, 16, v13
	v_and_b32_e32 v21, 0xffff0000, v13
	v_pk_mul_f32 v[16:17], v[20:21], v[16:17]
	v_lshlrev_b32_e32 v20, 16, v14
	v_cvt_pk_bf16_f32 v13, v16, v17
	v_lshlrev_b32_e32 v16, 16, v18
	v_and_b32_e32 v17, 0xffff0000, v18
	v_and_b32_e32 v21, 0xffff0000, v14
	v_pk_mul_f32 v[16:17], v[20:21], v[16:17]
	v_lshlrev_b32_e32 v18, 16, v15
	v_cvt_pk_bf16_f32 v14, v16, v17
	v_lshlrev_b32_e32 v16, 16, v19
	v_and_b32_e32 v17, 0xffff0000, v19
	v_and_b32_e32 v19, 0xffff0000, v15
	v_pk_mul_f32 v[16:17], v[18:19], v[16:17]
	s_waitcnt vmcnt(6)
	v_lshlrev_b32_e32 v18, 16, v8
	v_cvt_pk_bf16_f32 v15, v16, v17
	v_mad_i64_i32 v[16:17], s[0:1], v34, s2, v[28:29]
	v_lshl_add_u64 v[16:17], v[16:17], 0, v[192:193]
	global_store_dwordx4 v[16:17], v[12:15], off offset:2048 sc1
	ds_read_b128 v[12:15], v31 offset:5440
	v_and_b32_e32 v19, 0xffff0000, v8
	s_waitcnt lgkmcnt(0)
	v_lshlrev_b32_e32 v16, 16, v12
	v_and_b32_e32 v17, 0xffff0000, v12
	v_pk_mul_f32 v[16:17], v[18:19], v[16:17]
	v_lshlrev_b32_e32 v12, 16, v13
	v_cvt_pk_bf16_f32 v8, v16, v17
	v_and_b32_e32 v13, 0xffff0000, v13
	v_lshlrev_b32_e32 v16, 16, v9
	v_and_b32_e32 v17, 0xffff0000, v9
	v_pk_mul_f32 v[12:13], v[16:17], v[12:13]
	v_lshlrev_b32_e32 v16, 16, v10
	v_cvt_pk_bf16_f32 v9, v12, v13
	v_lshlrev_b32_e32 v12, 16, v14
	v_and_b32_e32 v13, 0xffff0000, v14
	v_and_b32_e32 v17, 0xffff0000, v10
	v_pk_mul_f32 v[12:13], v[16:17], v[12:13]
	v_lshlrev_b32_e32 v14, 16, v11
	v_cvt_pk_bf16_f32 v10, v12, v13
	v_lshlrev_b32_e32 v12, 16, v15
	v_and_b32_e32 v13, 0xffff0000, v15
	v_and_b32_e32 v15, 0xffff0000, v11
	v_pk_mul_f32 v[12:13], v[14:15], v[12:13]
	s_waitcnt vmcnt(6)
	v_lshlrev_b32_e32 v14, 16, v4
	v_cvt_pk_bf16_f32 v11, v12, v13
	v_mad_i64_i32 v[12:13], s[0:1], v33, s2, v[28:29]
	v_lshl_add_u64 v[12:13], v[12:13], 0, v[192:193]
	global_store_dwordx4 v[12:13], v[8:11], off offset:2048 sc1
	ds_read_b128 v[8:11], v31 offset:6528
	v_and_b32_e32 v15, 0xffff0000, v4
	s_waitcnt lgkmcnt(0)
	v_lshlrev_b32_e32 v12, 16, v8
	v_and_b32_e32 v13, 0xffff0000, v8
	v_pk_mul_f32 v[12:13], v[14:15], v[12:13]
	v_lshlrev_b32_e32 v8, 16, v9
	v_cvt_pk_bf16_f32 v4, v12, v13
	v_and_b32_e32 v9, 0xffff0000, v9
	v_lshlrev_b32_e32 v12, 16, v5
	v_and_b32_e32 v13, 0xffff0000, v5
	v_pk_mul_f32 v[8:9], v[12:13], v[8:9]
	v_lshlrev_b32_e32 v12, 16, v6
	v_cvt_pk_bf16_f32 v5, v8, v9
	v_lshlrev_b32_e32 v8, 16, v10
	v_and_b32_e32 v9, 0xffff0000, v10
	v_and_b32_e32 v13, 0xffff0000, v6
	v_pk_mul_f32 v[8:9], v[12:13], v[8:9]
	v_lshlrev_b32_e32 v10, 16, v7
	v_cvt_pk_bf16_f32 v6, v8, v9
	v_lshlrev_b32_e32 v8, 16, v11
	v_and_b32_e32 v9, 0xffff0000, v11
	v_and_b32_e32 v11, 0xffff0000, v7
	v_pk_mul_f32 v[8:9], v[10:11], v[8:9]
	s_waitcnt vmcnt(6)
	v_lshlrev_b32_e32 v10, 16, v0
	v_cvt_pk_bf16_f32 v7, v8, v9
	v_mad_i64_i32 v[8:9], s[0:1], v32, s2, v[28:29]
	v_lshl_add_u64 v[8:9], v[8:9], 0, v[192:193]
	global_store_dwordx4 v[8:9], v[4:7], off offset:2048 sc1
	ds_read_b128 v[4:7], v31 offset:7616
	v_and_b32_e32 v11, 0xffff0000, v0
	s_waitcnt lgkmcnt(0)
	v_lshlrev_b32_e32 v8, 16, v4
	v_and_b32_e32 v9, 0xffff0000, v4
	v_pk_mul_f32 v[8:9], v[10:11], v[8:9]
	v_lshlrev_b32_e32 v4, 16, v5
	v_cvt_pk_bf16_f32 v0, v8, v9
	v_and_b32_e32 v5, 0xffff0000, v5
	v_lshlrev_b32_e32 v8, 16, v1
	v_and_b32_e32 v9, 0xffff0000, v1
	v_pk_mul_f32 v[4:5], v[8:9], v[4:5]
	v_lshlrev_b32_e32 v8, 16, v2
	v_cvt_pk_bf16_f32 v1, v4, v5
	v_lshlrev_b32_e32 v4, 16, v6
	v_and_b32_e32 v5, 0xffff0000, v6
	v_and_b32_e32 v9, 0xffff0000, v2
	v_pk_mul_f32 v[4:5], v[8:9], v[4:5]
	v_lshlrev_b32_e32 v6, 16, v3
	v_cvt_pk_bf16_f32 v2, v4, v5
	v_lshlrev_b32_e32 v4, 16, v7
	v_and_b32_e32 v5, 0xffff0000, v7
	v_and_b32_e32 v7, 0xffff0000, v3
	v_pk_mul_f32 v[4:5], v[6:7], v[4:5]
	s_nop 0
	v_cvt_pk_bf16_f32 v3, v4, v5
	v_mad_i64_i32 v[4:5], s[0:1], v30, s2, v[28:29]
	s_mul_i32 s0, s62, s56
	s_add_i32 s0, s0, s57
	v_lshl_add_u64 v[4:5], v[4:5], 0, v[192:193]
	s_cmpk_gt_i32 s0, 0x1ff
	global_store_dwordx4 v[4:5], v[0:3], off offset:2048 sc1
	s_cbranch_scc1 .Lgq_restore
	.p2align	6

; __global__ void __launch_bounds__(512) mega(Args a) {
;     ...
;           bf16_t* dst = hh < 8 ? QBc + ((size_t)(b * 8 + hh) * SEQ + s) * 128 : (hh < 10 ? KBc + ((size_t)(b * 2 + hh - 8) * SEQ + s) * 128 : VBc + ((size_t)(b * 2 + hh - 10) * SEQ + s) * 128);
;           *(u32x4*)(dst + u * 8) = ov;
;         };
;         auto prep_src = [&](const int it) { const int tok = it / 3, hh = (it % 3) * 4 + sb; return (const u32x4*)(PROJ + (size_t)tok * NIN + C_QB + hh * 128 + u * 8); };
;         int it0 = gw;
;         for (; it0 + 3 * NGW < MT * 3; it0 += 4 * NGW) {
;           const u32x4 r0 = *prep_src(it0), r1 = *prep_src(it0 + NGW), r2 = *prep_src(it0 + 2 * NGW), r3 = *prep_src(it0 + 3 * NGW);
;           prep_item(it0, r0); prep_item(it0 + NGW, r1); prep_item(it0 + 2 * NGW, r2); prep_item(it0 + 3 * NGW, r3);
;         }
.LBB0_222:
	s_or_b64 exec, exec, s[0:1]
	v_ashrrev_i32_e32 v5, 31, v4
	v_lshlrev_b64 v[4:5], 21, v[4:5]
	v_lshl_add_u64 v[4:5], v[6:7], 0, v[4:5]
	v_lshlrev_b32_e32 v6, 8, v8
	v_mov_b32_e32 v7, v193
	v_lshl_add_u64 v[4:5], v[4:5], 0, v[6:7]
	v_lshl_add_u64 v[4:5], v[4:5], 0, v[192:193]
	v_add_u32_e32 v17, s19, v17
	s_waitcnt vmcnt(3)
	global_store_dwordx4 v[4:5], v[0:3], off
	s_mov_b32 s0, 0xbfff
	v_add_u32_e32 v18, s20, v18
	v_add_u32_e32 v0, s17, v17
	v_cmp_lt_i32_e32 vcc, s0, v0
	s_or_b64 s[46:47], vcc, s[46:47]
	v_add_u32_e32 v20, s21, v20
	s_andn2_b64 exec, exec, s[46:47]
	s_cbranch_execz .LBB0_265
	.p2align	6

; __device__ __forceinline__ unsigned cvt_pk_bf16(float lo, float hi) { f32x2_t v = {lo, hi}; bf16x2_t r = __builtin_convertvector(v, bf16x2_t); return __builtin_bit_cast(unsigned, r); }
; __device__ __forceinline__ int crow(int r, int hi) { return (r & 3) + 8 * (r >> 2) + 4 * hi; }
; template <int MODE, int SDEPTH, bool SIMPLE>
; __device__ __forceinline__ void attn_body(const Unit& U, char* lds, const int tid) {
;     ...
;   if (hi == 0) li_l[r32] = l_reg; asm volatile("s_waitcnt lgkmcnt(0)" ::: "memory");
;   if constexpr (MODE == 2) { if (hi == 0) U.LSE[(long)(wid * QBLK + r32) * U.ldl] = m_reg * SCALE + __logf(l_reg); }
;   __syncthreads();
;   constexpr int OP = 136;
;   bf16_t* ol = (bf16_t*)lds + wid * (32 * OP);
; #pragma unroll
;   for (int r = 0; r < 16; ++r) { const float rl = __builtin_amdgcn_rcpf(li_l[crow(r, hi)]); bf16_t* op = ol + crow(r, hi) * OP + r32;
; #pragma unroll
;     for (int d0 = 0; d0 < 4; ++d0) op[d0 * 32] = (bf16_t)(cvt_pk_bf16(o[d0][r] * rl, 0.f) & 0xffffu); }
.LBB0_281:
	s_or_b64 exec, exec, s[0:1]
	v_lshl_add_u32 v65, v156, 4, v157
	s_waitcnt lgkmcnt(0)
	s_waitcnt lgkmcnt(0)
	s_barrier
	ds_read_b128 v[66:69], v65
	s_mul_i32 s0, s3, 0x1400
	s_mul_hi_u32 s1, s20, 0x1400
	s_add_i32 s1, s1, s0
	s_mulk_i32 s20, 0x1400
	s_waitcnt lgkmcnt(0)
	v_rcp_f32_e32 v66, v66
	v_readlane_b32 s0, v250, 0
	s_movk_i32 s4, 0x2200
	s_add_u32 s0, s0, s20
	v_mul_lo_u32 v64, v158, s4
	s_addc_u32 s1, s19, s1
	s_lshl_b32 s2, s27, 1
	v_add_u32_e32 v64, 0, v64
	s_add_u32 s0, s0, s2
	v_lshl_add_u32 v70, v159, 1, v64
	s_movk_i32 s4, 0x440
	v_mul_f32_e32 v0, v0, v66
	v_mad_u32_u24 v71, v156, s4, v70
	v_cvt_pk_bf16_f32 v0, v0, s0
	ds_write_b16 v71, v0
	v_mul_f32_e32 v0, v48, v66
	v_cvt_pk_bf16_f32 v0, v0, s0
	ds_write_b16 v71, v0 offset:64
	v_mul_f32_e32 v0, v32, v66
	v_cvt_pk_bf16_f32 v0, v0, s0
	v_rcp_f32_e32 v32, v67
	ds_write_b16 v71, v0 offset:128
	v_mul_f32_e32 v0, v16, v66
	v_cvt_pk_bf16_f32 v0, v0, s0
	ds_write_b16 v71, v0 offset:192
	v_lshl_or_b32 v0, v156, 2, 1
	s_movk_i32 s4, 0x110
	v_mad_u32_u24 v16, v0, s4, v70
	v_mul_f32_e32 v0, v1, v32
	v_cvt_pk_bf16_f32 v0, v0, s0
	ds_write_b16 v16, v0
	v_mul_f32_e32 v0, v49, v32
	v_cvt_pk_bf16_f32 v0, v0, s0
	ds_write_b16 v16, v0 offset:64
	v_mul_f32_e32 v0, v33, v32
	v_cvt_pk_bf16_f32 v0, v0, s0
	ds_write_b16 v16, v0 offset:128
	v_mul_f32_e32 v0, v17, v32
	v_cvt_pk_bf16_f32 v0, v0, s0
	ds_write_b16 v16, v0 offset:192
	v_rcp_f32_e32 v0, v68
	s_addc_u32 s1, s1, 0
	s_add_u32 s2, s26, s2
	s_addc_u32 s3, s24, 0
	v_mul_f32_e32 v1, v2, v0
	v_cvt_pk_bf16_f32 v1, v1, s0
	ds_write_b16 v16, v1 offset:272
	v_mul_f32_e32 v1, v50, v0
	v_cvt_pk_bf16_f32 v1, v1, s0
	ds_write_b16 v16, v1 offset:336
	v_mul_f32_e32 v1, v34, v0
	v_mul_f32_e32 v0, v18, v0
	v_cvt_pk_bf16_f32 v0, v0, s0
	ds_write_b16 v16, v0 offset:464
	v_rcp_f32_e32 v0, v69
	v_cvt_pk_bf16_f32 v1, v1, s0
	ds_write_b16 v16, v1 offset:400
	s_add_i32 s21, s21, s16
	v_mul_f32_e32 v1, v3, v0
	v_cvt_pk_bf16_f32 v1, v1, s0
	ds_write_b16 v16, v1 offset:544
	v_mul_f32_e32 v1, v51, v0
	v_cvt_pk_bf16_f32 v1, v1, s0
	ds_write_b16 v16, v1 offset:608
	v_mul_f32_e32 v1, v35, v0
	v_mul_f32_e32 v0, v19, v0
	v_cvt_pk_bf16_f32 v1, v1, s0
	v_cvt_pk_bf16_f32 v0, v0, s0
	ds_write_b16 v16, v1 offset:672
	ds_write_b16 v16, v0 offset:736
	ds_read_b128 v[0:3], v65 offset:32
	s_movk_i32 s69, 0x1400
	s_waitcnt lgkmcnt(0)
	v_rcp_f32_e32 v0, v0
	s_nop 0
	v_mul_f32_e32 v4, v4, v0
	v_cvt_pk_bf16_f32 v4, v4, s0
	ds_write_b16 v16, v4 offset:1904
	v_mul_f32_e32 v4, v52, v0
	v_cvt_pk_bf16_f32 v4, v4, s0
	ds_write_b16 v16, v4 offset:1968
	v_mul_f32_e32 v4, v36, v0
	v_mul_f32_e32 v0, v20, v0
	v_cvt_pk_bf16_f32 v0, v0, s0
	ds_write_b16 v16, v0 offset:2096
	v_rcp_f32_e32 v0, v1
	v_cvt_pk_bf16_f32 v4, v4, s0
	ds_write_b16 v16, v4 offset:2032
	v_mul_f32_e32 v1, v5, v0
	v_cvt_pk_bf16_f32 v1, v1, s0
	ds_write_b16 v16, v1 offset:2176
	v_mul_f32_e32 v1, v53, v0
	v_cvt_pk_bf16_f32 v1, v1, s0
	ds_write_b16 v16, v1 offset:2240
	v_mul_f32_e32 v1, v37, v0
	v_mul_f32_e32 v0, v21, v0
	v_cvt_pk_bf16_f32 v0, v0, s0
	ds_write_b16 v16, v0 offset:2368
	v_rcp_f32_e32 v0, v2
	v_cvt_pk_bf16_f32 v1, v1, s0
	ds_write_b16 v16, v1 offset:2304
	v_mul_f32_e32 v1, v6, v0
	v_cvt_pk_bf16_f32 v1, v1, s0
	ds_write_b16 v16, v1 offset:2448
	v_mul_f32_e32 v1, v54, v0
	v_cvt_pk_bf16_f32 v1, v1, s0
	ds_write_b16 v16, v1 offset:2512
	v_mul_f32_e32 v1, v38, v0
	v_mul_f32_e32 v0, v22, v0
	v_cvt_pk_bf16_f32 v0, v0, s0
	ds_write_b16 v16, v0 offset:2640
	v_rcp_f32_e32 v0, v3
	v_cvt_pk_bf16_f32 v1, v1, s0
	ds_write_b16 v16, v1 offset:2576
	v_mul_f32_e32 v1, v7, v0
	v_cvt_pk_bf16_f32 v1, v1, s0
	ds_write_b16 v16, v1 offset:2720
	v_mul_f32_e32 v1, v55, v0
	v_cvt_pk_bf16_f32 v1, v1, s0
	ds_write_b16 v16, v1 offset:2784
	v_mul_f32_e32 v1, v39, v0
	v_mul_f32_e32 v0, v23, v0
	v_cvt_pk_bf16_f32 v1, v1, s0
	v_cvt_pk_bf16_f32 v0, v0, s0
	ds_write_b16 v16, v1 offset:2848
	ds_write_b16 v16, v0 offset:2912
	ds_read_b128 v[0:3], v65 offset:64
	s_waitcnt lgkmcnt(0)
	v_rcp_f32_e32 v0, v0
	s_nop 0
	v_mul_f32_e32 v4, v8, v0
	v_cvt_pk_bf16_f32 v4, v4, s0
	ds_write_b16 v16, v4 offset:4080
	v_mul_f32_e32 v4, v56, v0
	v_cvt_pk_bf16_f32 v4, v4, s0
	ds_write_b16 v16, v4 offset:4144
	v_mul_f32_e32 v4, v40, v0
	v_mul_f32_e32 v0, v24, v0
	v_cvt_pk_bf16_f32 v0, v0, s0
	ds_write_b16 v16, v0 offset:4272
	v_rcp_f32_e32 v0, v1
	v_cvt_pk_bf16_f32 v4, v4, s0
	ds_write_b16 v16, v4 offset:4208
	v_mul_f32_e32 v1, v9, v0
	v_cvt_pk_bf16_f32 v1, v1, s0
	ds_write_b16 v16, v1 offset:4352
	v_mul_f32_e32 v1, v57, v0
	v_cvt_pk_bf16_f32 v1, v1, s0
	ds_write_b16 v16, v1 offset:4416
	v_mul_f32_e32 v1, v41, v0
	v_mul_f32_e32 v0, v25, v0
	v_cvt_pk_bf16_f32 v0, v0, s0
	ds_write_b16 v16, v0 offset:4544
	v_rcp_f32_e32 v0, v2
	v_cvt_pk_bf16_f32 v1, v1, s0
	ds_write_b16 v16, v1 offset:4480
	v_mul_f32_e32 v1, v10, v0
	v_cvt_pk_bf16_f32 v1, v1, s0
	ds_write_b16 v16, v1 offset:4624
	v_mul_f32_e32 v1, v58, v0
	v_cvt_pk_bf16_f32 v1, v1, s0
	ds_write_b16 v16, v1 offset:4688
	v_mul_f32_e32 v1, v42, v0
	v_mul_f32_e32 v0, v26, v0
	v_cvt_pk_bf16_f32 v0, v0, s0
	ds_write_b16 v16, v0 offset:4816
	v_rcp_f32_e32 v0, v3
	v_cvt_pk_bf16_f32 v1, v1, s0
	ds_write_b16 v16, v1 offset:4752
	v_mul_f32_e32 v1, v11, v0
	v_cvt_pk_bf16_f32 v1, v1, s0
	ds_write_b16 v16, v1 offset:4896
	v_mul_f32_e32 v1, v59, v0
	v_cvt_pk_bf16_f32 v1, v1, s0
	ds_write_b16 v16, v1 offset:4960
	v_mul_f32_e32 v1, v43, v0
	v_mul_f32_e32 v0, v27, v0
	v_cvt_pk_bf16_f32 v1, v1, s0
	v_cvt_pk_bf16_f32 v0, v0, s0
	ds_write_b16 v16, v1 offset:5024
	ds_write_b16 v16, v0 offset:5088
	ds_read_b128 v[0:3], v65 offset:96
	s_waitcnt lgkmcnt(0)
; __device__ __forceinline__ unsigned cvt_pk_bf16(float lo, float hi) { f32x2_t v = {lo, hi}; bf16x2_t r = __builtin_convertvector(v, bf16x2_t); return __builtin_bit_cast(unsigned, r); }
; __device__ __forceinline__ float bf_lo(unsigned w) { return __uint_as_float(w << 16); }
; __device__ __forceinline__ float bf_hi(unsigned w) { return __uint_as_float(w & 0xffff0000u); }
; __device__ __forceinline__ int crow(int r, int hi) { return (r & 3) + 8 * (r >> 2) + 4 * hi; }
; template <int MODE, int SDEPTH, bool SIMPLE>
; __device__ __forceinline__ void attn_body(const Unit& U, char* lds, const int tid) {
;     ...
;   for (int r = 0; r < 16; ++r) { const float rl = __builtin_amdgcn_rcpf(li_l[crow(r, hi)]); bf16_t* op = ol + crow(r, hi) * OP + r32;
; #pragma unroll
;     for (int d0 = 0; d0 < 4; ++d0) op[d0 * 32] = (bf16_t)(cvt_pk_bf16(o[d0][r] * rl, 0.f) & 0xffffu); }
;   asm volatile("s_waitcnt lgkmcnt(0)" ::: "memory");
;   { const int cc = (lane & 15) * 8, rb = lane >> 4;
;     u32x4 zz[8];
;     if constexpr (MODE != 2) {
; #pragma unroll
;       for (int i = 0; i < 8; ++i) zz[i] = *(const u32x4*)(U.Z + (long)(wid * QBLK + rb + 4 * i) * U.ldz + cc);
;     }
; #pragma unroll
;     for (int i = 0; i < 8; ++i) { const int row = rb + 4 * i; const long orow = wid * QBLK + row;
;       u32x4 v = *(const u32x4*)(ol + row * OP + cc);
;       if constexpr (MODE != 2) { const u32x4 z = zz[i];
; #pragma unroll
;         for (int q = 0; q < 4; ++q) v[q] = cvt_pk_bf16(bf_lo(v[q]) * bf_lo(z[q]), bf_hi(v[q]) * bf_hi(z[q])); }
;       *(u32x4*)(U.O + orow * U.ldo + cc) = v; } }
	v_rcp_f32_e32 v0, v0
	s_nop 0
	v_mul_f32_e32 v4, v12, v0
	v_cvt_pk_bf16_f32 v4, v4, s0
	ds_write_b16 v16, v4 offset:6256
	v_mul_f32_e32 v4, v60, v0
	v_cvt_pk_bf16_f32 v4, v4, s0
	ds_write_b16 v16, v4 offset:6320
	v_mul_f32_e32 v4, v44, v0
	v_mul_f32_e32 v0, v28, v0
	v_cvt_pk_bf16_f32 v0, v0, s0
	ds_write_b16 v16, v0 offset:6448
	v_rcp_f32_e32 v0, v1
	v_cvt_pk_bf16_f32 v4, v4, s0
	v_lshrrev_b32_e32 v28, 4, v154
	ds_write_b16 v16, v4 offset:6384
	v_mul_f32_e32 v1, v13, v0
	v_cvt_pk_bf16_f32 v1, v1, s0
	ds_write_b16 v16, v1 offset:6528
	v_mul_f32_e32 v1, v61, v0
	v_cvt_pk_bf16_f32 v1, v1, s0
	ds_write_b16 v16, v1 offset:6592
	v_mul_f32_e32 v1, v45, v0
	v_mul_f32_e32 v0, v29, v0
	v_cvt_pk_bf16_f32 v0, v0, s0
	ds_write_b16 v16, v0 offset:6720
	v_rcp_f32_e32 v0, v2
	v_cvt_pk_bf16_f32 v1, v1, s0
	ds_write_b16 v16, v1 offset:6656
	v_mul_f32_e32 v1, v14, v0
	v_cvt_pk_bf16_f32 v1, v1, s0
	ds_write_b16 v16, v1 offset:6800
	v_mul_f32_e32 v1, v62, v0
	v_cvt_pk_bf16_f32 v1, v1, s0
	ds_write_b16 v16, v1 offset:6864
	v_mul_f32_e32 v1, v46, v0
	v_mul_f32_e32 v0, v30, v0
	v_cvt_pk_bf16_f32 v0, v0, s0
	ds_write_b16 v16, v0 offset:6992
	v_rcp_f32_e32 v0, v3
	v_cvt_pk_bf16_f32 v1, v1, s0
	ds_write_b16 v16, v1 offset:6928
	v_or_b32_e32 v46, v28, v155
	v_mul_f32_e32 v1, v15, v0
	v_cvt_pk_bf16_f32 v1, v1, s0
	ds_write_b16 v16, v1 offset:7072
	v_mul_f32_e32 v1, v63, v0
	v_cvt_pk_bf16_f32 v1, v1, s0
	ds_write_b16 v16, v1 offset:7136
	v_mul_f32_e32 v1, v47, v0
	v_mul_f32_e32 v0, v31, v0
	v_cvt_pk_bf16_f32 v1, v1, s0
	v_cvt_pk_bf16_f32 v0, v0, s0
	ds_write_b16 v16, v1 offset:7200
	ds_write_b16 v16, v0 offset:7264
	v_lshl_add_u64 v[0:1], s[2:3], 0, v[192:193]
	s_mov_b64 s[2:3], 0x4800
	v_lshl_add_u64 v[0:1], v[0:1], 0, s[2:3]
	s_waitcnt lgkmcnt(0)
	v_mad_i64_i32 v[2:3], s[2:3], v46, s14, v[0:1]
	global_load_dwordx4 v[36:39], v[2:3], off
	v_or_b32_e32 v47, 4, v46
	v_mad_i64_i32 v[2:3], s[2:3], v47, s14, v[0:1]
	global_load_dwordx4 v[24:27], v[2:3], off
	v_or_b32_e32 v48, 8, v46
	v_mad_i64_i32 v[2:3], s[2:3], v48, s14, v[0:1]
	global_load_dwordx4 v[20:23], v[2:3], off
	v_or_b32_e32 v35, 12, v46
	v_mad_i64_i32 v[2:3], s[2:3], v35, s14, v[0:1]
	global_load_dwordx4 v[16:19], v[2:3], off
	v_or_b32_e32 v34, 16, v46
	v_mad_i64_i32 v[2:3], s[2:3], v34, s14, v[0:1]
	global_load_dwordx4 v[12:15], v[2:3], off
	v_mul_u32_u24_e32 v28, 0x110, v28
	v_or_b32_e32 v33, 20, v46
	v_add3_u32 v31, v64, v192, v28
	v_mad_i64_i32 v[2:3], s[2:3], v33, s14, v[0:1]
	ds_read_b128 v[40:43], v31
	global_load_dwordx4 v[8:11], v[2:3], off
	v_or_b32_e32 v32, 24, v46
	v_or_b32_e32 v30, 28, v46
	v_mad_i64_i32 v[2:3], s[2:3], v32, s14, v[0:1]
	s_waitcnt lgkmcnt(0)
	v_lshlrev_b32_e32 v28, 16, v40
	v_and_b32_e32 v29, 0xffff0000, v40
	v_mad_i64_i32 v[0:1], s[2:3], v30, s14, v[0:1]
	s_movk_i32 s2, 0x1400
	global_load_dwordx4 v[4:7], v[2:3], off
	s_waitcnt vmcnt(6)
	v_lshlrev_b32_e32 v44, 16, v36
	v_and_b32_e32 v45, 0xffff0000, v36
	v_pk_mul_f32 v[28:29], v[44:45], v[28:29]
	v_lshlrev_b32_e32 v40, 16, v37
	v_cvt_pk_bf16_f32 v36, v28, v29
	v_lshlrev_b32_e32 v28, 16, v41
	v_and_b32_e32 v29, 0xffff0000, v41
	v_and_b32_e32 v41, 0xffff0000, v37
	v_pk_mul_f32 v[28:29], v[40:41], v[28:29]
	v_lshlrev_b32_e32 v40, 16, v38
	v_cvt_pk_bf16_f32 v37, v28, v29
	v_lshlrev_b32_e32 v28, 16, v42
	v_and_b32_e32 v29, 0xffff0000, v42
	v_and_b32_e32 v41, 0xffff0000, v38
	v_pk_mul_f32 v[28:29], v[40:41], v[28:29]
	v_lshlrev_b32_e32 v40, 16, v39
	v_cvt_pk_bf16_f32 v38, v28, v29
	v_lshlrev_b32_e32 v28, 16, v43
	v_and_b32_e32 v29, 0xffff0000, v43
	v_and_b32_e32 v41, 0xffff0000, v39
	v_pk_mul_f32 v[28:29], v[40:41], v[28:29]
	global_load_dwordx4 v[0:3], v[0:1], off
	v_cvt_pk_bf16_f32 v39, v28, v29
	v_mov_b64_e32 v[28:29], s[0:1]
	v_mad_i64_i32 v[40:41], s[0:1], v46, s2, v[28:29]
	v_lshl_add_u64 v[40:41], v[40:41], 0, v[192:193]
	global_store_dwordx4 v[40:41], v[36:39], off sc1
	ds_read_b128 v[36:39], v31 offset:1088
	s_waitcnt vmcnt(7)
	v_lshlrev_b32_e32 v42, 16, v24
	v_and_b32_e32 v43, 0xffff0000, v24
	s_waitcnt lgkmcnt(0)
	v_lshlrev_b32_e32 v40, 16, v36
	v_and_b32_e32 v41, 0xffff0000, v36
	v_pk_mul_f32 v[40:41], v[42:43], v[40:41]
	v_lshlrev_b32_e32 v36, 16, v37
	v_cvt_pk_bf16_f32 v24, v40, v41
	v_and_b32_e32 v37, 0xffff0000, v37
	v_lshlrev_b32_e32 v40, 16, v25
	v_and_b32_e32 v41, 0xffff0000, v25
	v_pk_mul_f32 v[36:37], v[40:41], v[36:37]
	v_lshlrev_b32_e32 v40, 16, v26
	v_cvt_pk_bf16_f32 v25, v36, v37
	v_lshlrev_b32_e32 v36, 16, v38
	v_and_b32_e32 v37, 0xffff0000, v38
	v_and_b32_e32 v41, 0xffff0000, v26
	v_pk_mul_f32 v[36:37], v[40:41], v[36:37]
	v_lshlrev_b32_e32 v38, 16, v27
	v_cvt_pk_bf16_f32 v26, v36, v37
	v_lshlrev_b32_e32 v36, 16, v39
	v_and_b32_e32 v37, 0xffff0000, v39
	v_and_b32_e32 v39, 0xffff0000, v27
	v_pk_mul_f32 v[36:37], v[38:39], v[36:37]
	s_waitcnt vmcnt(6)
	v_lshlrev_b32_e32 v38, 16, v20
	v_cvt_pk_bf16_f32 v27, v36, v37
	v_mad_i64_i32 v[36:37], s[0:1], v47, s2, v[28:29]
	v_lshl_add_u64 v[36:37], v[36:37], 0, v[192:193]
	global_store_dwordx4 v[36:37], v[24:27], off sc1
	ds_read_b128 v[24:27], v31 offset:2176
	v_and_b32_e32 v39, 0xffff0000, v20
	s_waitcnt lgkmcnt(0)
	v_lshlrev_b32_e32 v36, 16, v24
	v_and_b32_e32 v37, 0xffff0000, v24
	v_pk_mul_f32 v[36:37], v[38:39], v[36:37]
	v_lshlrev_b32_e32 v24, 16, v25
	v_cvt_pk_bf16_f32 v20, v36, v37
	v_and_b32_e32 v25, 0xffff0000, v25
	v_lshlrev_b32_e32 v36, 16, v21
	v_and_b32_e32 v37, 0xffff0000, v21
	v_pk_mul_f32 v[24:25], v[36:37], v[24:25]
	v_lshlrev_b32_e32 v36, 16, v22
	v_cvt_pk_bf16_f32 v21, v24, v25
	v_lshlrev_b32_e32 v24, 16, v26
	v_and_b32_e32 v25, 0xffff0000, v26
	v_and_b32_e32 v37, 0xffff0000, v22
	v_pk_mul_f32 v[24:25], v[36:37], v[24:25]
	v_lshlrev_b32_e32 v26, 16, v23
	v_cvt_pk_bf16_f32 v22, v24, v25
	v_lshlrev_b32_e32 v24, 16, v27
	v_and_b32_e32 v25, 0xffff0000, v27
	v_and_b32_e32 v27, 0xffff0000, v23
	v_pk_mul_f32 v[24:25], v[26:27], v[24:25]
	s_waitcnt vmcnt(6)
; __device__ __forceinline__ unsigned cvt_pk_bf16(float lo, float hi) { f32x2_t v = {lo, hi}; bf16x2_t r = __builtin_convertvector(v, bf16x2_t); return __builtin_bit_cast(unsigned, r); }
; __device__ __forceinline__ float bf_lo(unsigned w) { return __uint_as_float(w << 16); }
; __device__ __forceinline__ float bf_hi(unsigned w) { return __uint_as_float(w & 0xffff0000u); }
; template <int MODE, int SDEPTH, bool SIMPLE>
; __device__ __forceinline__ void attn_body(const Unit& U, char* lds, const int tid) {
;     ...
;       for (int i = 0; i < 8; ++i) zz[i] = *(const u32x4*)(U.Z + (long)(wid * QBLK + rb + 4 * i) * U.ldz + cc);
;     }
; #pragma unroll
;     for (int i = 0; i < 8; ++i) { const int row = rb + 4 * i; const long orow = wid * QBLK + row;
;       u32x4 v = *(const u32x4*)(ol + row * OP + cc);
;       if constexpr (MODE != 2) { const u32x4 z = zz[i];
; #pragma unroll
;         for (int q = 0; q < 4; ++q) v[q] = cvt_pk_bf16(bf_lo(v[q]) * bf_lo(z[q]), bf_hi(v[q]) * bf_hi(z[q])); }
;       *(u32x4*)(U.O + orow * U.ldo + cc) = v; } }
; __global__ void __launch_bounds__(512) mega(Args a) {
;     ...
;       if (P2MASK & 2) for (int un = cu; un < NB * 8 * 32; un += G) {
	v_lshlrev_b32_e32 v26, 16, v16
	v_cvt_pk_bf16_f32 v23, v24, v25
	v_mad_i64_i32 v[24:25], s[0:1], v48, s2, v[28:29]
	v_lshl_add_u64 v[24:25], v[24:25], 0, v[192:193]
	global_store_dwordx4 v[24:25], v[20:23], off sc1
	ds_read_b128 v[20:23], v31 offset:3264
	v_and_b32_e32 v27, 0xffff0000, v16
	s_waitcnt lgkmcnt(0)
	v_lshlrev_b32_e32 v24, 16, v20
	v_and_b32_e32 v25, 0xffff0000, v20
	v_pk_mul_f32 v[24:25], v[26:27], v[24:25]
	v_lshlrev_b32_e32 v20, 16, v21
	v_cvt_pk_bf16_f32 v16, v24, v25
	v_and_b32_e32 v21, 0xffff0000, v21
	v_lshlrev_b32_e32 v24, 16, v17
	v_and_b32_e32 v25, 0xffff0000, v17
	v_pk_mul_f32 v[20:21], v[24:25], v[20:21]
	v_lshlrev_b32_e32 v24, 16, v18
	v_cvt_pk_bf16_f32 v17, v20, v21
	v_lshlrev_b32_e32 v20, 16, v22
	v_and_b32_e32 v21, 0xffff0000, v22
	v_and_b32_e32 v25, 0xffff0000, v18
	v_pk_mul_f32 v[20:21], v[24:25], v[20:21]
	v_lshlrev_b32_e32 v22, 16, v19
	v_cvt_pk_bf16_f32 v18, v20, v21
	v_lshlrev_b32_e32 v20, 16, v23
	v_and_b32_e32 v21, 0xffff0000, v23
	v_and_b32_e32 v23, 0xffff0000, v19
	v_pk_mul_f32 v[20:21], v[22:23], v[20:21]
	s_waitcnt vmcnt(6)
	v_lshlrev_b32_e32 v22, 16, v12
	v_cvt_pk_bf16_f32 v19, v20, v21
	v_mad_i64_i32 v[20:21], s[0:1], v35, s2, v[28:29]
	v_lshl_add_u64 v[20:21], v[20:21], 0, v[192:193]
	global_store_dwordx4 v[20:21], v[16:19], off sc1
	ds_read_b128 v[16:19], v31 offset:4352
	v_and_b32_e32 v23, 0xffff0000, v12
	s_waitcnt lgkmcnt(0)
	v_lshlrev_b32_e32 v20, 16, v16
	v_and_b32_e32 v21, 0xffff0000, v16
	v_pk_mul_f32 v[20:21], v[22:23], v[20:21]
	v_lshlrev_b32_e32 v16, 16, v17
	v_cvt_pk_bf16_f32 v12, v20, v21
	v_and_b32_e32 v17, 0xffff0000, v17
	v_lshlrev_b32_e32 v20, 16, v13
	v_and_b32_e32 v21, 0xffff0000, v13
	v_pk_mul_f32 v[16:17], v[20:21], v[16:17]
	v_lshlrev_b32_e32 v20, 16, v14
	v_cvt_pk_bf16_f32 v13, v16, v17
	v_lshlrev_b32_e32 v16, 16, v18
	v_and_b32_e32 v17, 0xffff0000, v18
	v_and_b32_e32 v21, 0xffff0000, v14
	v_pk_mul_f32 v[16:17], v[20:21], v[16:17]
	v_lshlrev_b32_e32 v18, 16, v15
	v_cvt_pk_bf16_f32 v14, v16, v17
	v_lshlrev_b32_e32 v16, 16, v19
	v_and_b32_e32 v17, 0xffff0000, v19
	v_and_b32_e32 v19, 0xffff0000, v15
	v_pk_mul_f32 v[16:17], v[18:19], v[16:17]
	s_waitcnt vmcnt(6)
	v_lshlrev_b32_e32 v18, 16, v8
	v_cvt_pk_bf16_f32 v15, v16, v17
	v_mad_i64_i32 v[16:17], s[0:1], v34, s2, v[28:29]
	v_lshl_add_u64 v[16:17], v[16:17], 0, v[192:193]
	global_store_dwordx4 v[16:17], v[12:15], off sc1
	ds_read_b128 v[12:15], v31 offset:5440
	v_and_b32_e32 v19, 0xffff0000, v8
	s_waitcnt lgkmcnt(0)
	v_lshlrev_b32_e32 v16, 16, v12
	v_and_b32_e32 v17, 0xffff0000, v12
	v_pk_mul_f32 v[16:17], v[18:19], v[16:17]
	v_lshlrev_b32_e32 v12, 16, v13
	v_cvt_pk_bf16_f32 v8, v16, v17
	v_and_b32_e32 v13, 0xffff0000, v13
	v_lshlrev_b32_e32 v16, 16, v9
	v_and_b32_e32 v17, 0xffff0000, v9
	v_pk_mul_f32 v[12:13], v[16:17], v[12:13]
	v_lshlrev_b32_e32 v16, 16, v10
	v_cvt_pk_bf16_f32 v9, v12, v13
	v_lshlrev_b32_e32 v12, 16, v14
	v_and_b32_e32 v13, 0xffff0000, v14
	v_and_b32_e32 v17, 0xffff0000, v10
	v_pk_mul_f32 v[12:13], v[16:17], v[12:13]
	v_lshlrev_b32_e32 v14, 16, v11
	v_cvt_pk_bf16_f32 v10, v12, v13
	v_lshlrev_b32_e32 v12, 16, v15
	v_and_b32_e32 v13, 0xffff0000, v15
	v_and_b32_e32 v15, 0xffff0000, v11
	v_pk_mul_f32 v[12:13], v[14:15], v[12:13]
	s_waitcnt vmcnt(6)
	v_lshlrev_b32_e32 v14, 16, v4
	v_cvt_pk_bf16_f32 v11, v12, v13
	v_mad_i64_i32 v[12:13], s[0:1], v33, s2, v[28:29]
	v_lshl_add_u64 v[12:13], v[12:13], 0, v[192:193]
	global_store_dwordx4 v[12:13], v[8:11], off sc1
	ds_read_b128 v[8:11], v31 offset:6528
	v_and_b32_e32 v15, 0xffff0000, v4
	s_waitcnt lgkmcnt(0)
	v_lshlrev_b32_e32 v12, 16, v8
	v_and_b32_e32 v13, 0xffff0000, v8
	v_pk_mul_f32 v[12:13], v[14:15], v[12:13]
	v_lshlrev_b32_e32 v8, 16, v9
	v_cvt_pk_bf16_f32 v4, v12, v13
	v_and_b32_e32 v9, 0xffff0000, v9
	v_lshlrev_b32_e32 v12, 16, v5
	v_and_b32_e32 v13, 0xffff0000, v5
	v_pk_mul_f32 v[8:9], v[12:13], v[8:9]
	v_lshlrev_b32_e32 v12, 16, v6
	v_cvt_pk_bf16_f32 v5, v8, v9
	v_lshlrev_b32_e32 v8, 16, v10
	v_and_b32_e32 v9, 0xffff0000, v10
	v_and_b32_e32 v13, 0xffff0000, v6
	v_pk_mul_f32 v[8:9], v[12:13], v[8:9]
	v_lshlrev_b32_e32 v10, 16, v7
	v_cvt_pk_bf16_f32 v6, v8, v9
	v_lshlrev_b32_e32 v8, 16, v11
	v_and_b32_e32 v9, 0xffff0000, v11
	v_and_b32_e32 v11, 0xffff0000, v7
	v_pk_mul_f32 v[8:9], v[10:11], v[8:9]
	s_waitcnt vmcnt(6)
	v_lshlrev_b32_e32 v10, 16, v0
	v_cvt_pk_bf16_f32 v7, v8, v9
	v_mad_i64_i32 v[8:9], s[0:1], v32, s2, v[28:29]
	v_lshl_add_u64 v[8:9], v[8:9], 0, v[192:193]
	global_store_dwordx4 v[8:9], v[4:7], off sc1
	ds_read_b128 v[4:7], v31 offset:7616
	v_and_b32_e32 v11, 0xffff0000, v0
	s_waitcnt lgkmcnt(0)
	v_lshlrev_b32_e32 v8, 16, v4
	v_and_b32_e32 v9, 0xffff0000, v4
	v_pk_mul_f32 v[8:9], v[10:11], v[8:9]
	v_lshlrev_b32_e32 v4, 16, v5
	v_cvt_pk_bf16_f32 v0, v8, v9
	v_and_b32_e32 v5, 0xffff0000, v5
	v_lshlrev_b32_e32 v8, 16, v1
	v_and_b32_e32 v9, 0xffff0000, v1
	v_pk_mul_f32 v[4:5], v[8:9], v[4:5]
	v_lshlrev_b32_e32 v8, 16, v2
	v_cvt_pk_bf16_f32 v1, v4, v5
	v_lshlrev_b32_e32 v4, 16, v6
	v_and_b32_e32 v5, 0xffff0000, v6
	v_and_b32_e32 v9, 0xffff0000, v2
	v_pk_mul_f32 v[4:5], v[8:9], v[4:5]
	v_lshlrev_b32_e32 v6, 16, v3
	v_cvt_pk_bf16_f32 v2, v4, v5
	v_lshlrev_b32_e32 v4, 16, v7
	v_and_b32_e32 v5, 0xffff0000, v7
	v_and_b32_e32 v7, 0xffff0000, v3
	v_pk_mul_f32 v[4:5], v[6:7], v[4:5]
	s_nop 0
	v_cvt_pk_bf16_f32 v3, v4, v5
	v_mad_i64_i32 v[4:5], s[0:1], v30, s2, v[28:29]
	v_readlane_b32 s0, v251, 63
	v_readlane_b32 s17, v250, 31
	s_add_i32 s17, s17, s0
	v_writelane_b32 v250, s17, 31
	v_lshl_add_u64 v[4:5], v[4:5], 0, v[192:193]
	s_cmpk_gt_i32 s17, 0x1ff
	global_store_dwordx4 v[4:5], v[0:3], off sc1
	s_cbranch_scc1 .LBB0_298
	.p2align	6

; __device__ __forceinline__ unsigned cvt_pk_bf16(float lo, float hi) { f32x2_t v = {lo, hi}; bf16x2_t r = __builtin_convertvector(v, bf16x2_t); return __builtin_bit_cast(unsigned, r); }
; __device__ __forceinline__ int crow(int r, int hi) { return (r & 3) + 8 * (r >> 2) + 4 * hi; }
; template <int MODE, int SDEPTH, bool SIMPLE>
; __device__ __forceinline__ void attn_body(const Unit& U, char* lds, const int tid) {
;     ...
;   if (hi == 0) li_l[r32] = l_reg; asm volatile("s_waitcnt lgkmcnt(0)" ::: "memory");
;   if constexpr (MODE == 2) { if (hi == 0) U.LSE[(long)(wid * QBLK + r32) * U.ldl] = m_reg * SCALE + __logf(l_reg); }
;   __syncthreads();
;   constexpr int OP = 136;
;   bf16_t* ol = (bf16_t*)lds + wid * (32 * OP);
; #pragma unroll
;   for (int r = 0; r < 16; ++r) { const float rl = __builtin_amdgcn_rcpf(li_l[crow(r, hi)]); bf16_t* op = ol + crow(r, hi) * OP + r32;
; #pragma unroll
;     for (int d0 = 0; d0 < 4; ++d0) op[d0 * 32] = (bf16_t)(cvt_pk_bf16(o[d0][r] * rl, 0.f) & 0xffffu); }
.LBB0_300:
	s_or_b64 exec, exec, s[36:37]
	v_lshl_add_u32 v65, v155, 4, v156
	s_waitcnt lgkmcnt(0)
	s_barrier
	ds_read_b128 v[66:69], v65
	s_lshl_b64 s[0:1], s[2:3], 10
	s_add_u32 s0, s16, s0
	s_addc_u32 s1, s17, s1
	s_lshl_b32 s2, s27, 8
	s_waitcnt lgkmcnt(0)
	v_rcp_f32_e32 v66, v66
	s_add_u32 s0, s0, s2
	s_movk_i32 s2, 0x2200
	v_mul_lo_u32 v64, v157, s2
	v_add_u32_e32 v64, 0, v64
	v_lshl_add_u32 v70, v158, 1, v64
	s_movk_i32 s2, 0x440
	v_mul_f32_e32 v0, v0, v66
	v_mad_u32_u24 v71, v155, s2, v70
	v_cvt_pk_bf16_f32 v0, v0, s0
	ds_write_b16 v71, v0
	v_mul_f32_e32 v0, v48, v66
	v_cvt_pk_bf16_f32 v0, v0, s0
	ds_write_b16 v71, v0 offset:64
	v_mul_f32_e32 v0, v32, v66
	v_cvt_pk_bf16_f32 v0, v0, s0
	v_rcp_f32_e32 v32, v67
	ds_write_b16 v71, v0 offset:128
	v_mul_f32_e32 v0, v16, v66
	v_cvt_pk_bf16_f32 v0, v0, s0
	ds_write_b16 v71, v0 offset:192
	v_lshl_or_b32 v0, v155, 2, 1
	s_movk_i32 s2, 0x110
	v_mad_u32_u24 v16, v0, s2, v70
	v_mul_f32_e32 v0, v1, v32
	v_cvt_pk_bf16_f32 v0, v0, s0
	ds_write_b16 v16, v0
	v_mul_f32_e32 v0, v49, v32
	v_cvt_pk_bf16_f32 v0, v0, s0
	ds_write_b16 v16, v0 offset:64
	v_mul_f32_e32 v0, v33, v32
	v_cvt_pk_bf16_f32 v0, v0, s0
	ds_write_b16 v16, v0 offset:128
	v_mul_f32_e32 v0, v17, v32
	v_cvt_pk_bf16_f32 v0, v0, s0
	ds_write_b16 v16, v0 offset:192
	v_rcp_f32_e32 v0, v68
	s_addc_u32 s1, s1, 0
	s_and_b64 s[2:3], s[4:5], exec
	s_cselect_b32 s4, 11, 13
	v_mul_f32_e32 v1, v2, v0
	v_cvt_pk_bf16_f32 v1, v1, s0
	ds_write_b16 v16, v1 offset:272
	v_mul_f32_e32 v1, v50, v0
	v_cvt_pk_bf16_f32 v1, v1, s0
	ds_write_b16 v16, v1 offset:336
	v_mul_f32_e32 v1, v34, v0
	v_mul_f32_e32 v0, v18, v0
	v_cvt_pk_bf16_f32 v0, v0, s0
	ds_write_b16 v16, v0 offset:464
	v_rcp_f32_e32 v0, v69
	v_cvt_pk_bf16_f32 v1, v1, s0
	ds_write_b16 v16, v1 offset:400
	s_and_b64 s[2:3], s[8:9], exec
	v_mul_f32_e32 v1, v3, v0
	v_cvt_pk_bf16_f32 v1, v1, s0
	ds_write_b16 v16, v1 offset:544
	v_mul_f32_e32 v1, v51, v0
	v_cvt_pk_bf16_f32 v1, v1, s0
	ds_write_b16 v16, v1 offset:608
	v_mul_f32_e32 v1, v35, v0
	v_mul_f32_e32 v0, v19, v0
	v_cvt_pk_bf16_f32 v1, v1, s0
	v_cvt_pk_bf16_f32 v0, v0, s0
	ds_write_b16 v16, v1 offset:672
	ds_write_b16 v16, v0 offset:736
	ds_read_b128 v[0:3], v65 offset:32
	s_cselect_b32 s2, 9, s4
	s_add_i32 s21, s21, s23
	s_waitcnt lgkmcnt(0)
	v_rcp_f32_e32 v0, v0
	s_nop 0
	v_mul_f32_e32 v4, v4, v0
	v_cvt_pk_bf16_f32 v4, v4, s0
	ds_write_b16 v16, v4 offset:1904
	v_mul_f32_e32 v4, v52, v0
	v_cvt_pk_bf16_f32 v4, v4, s0
	ds_write_b16 v16, v4 offset:1968
	v_mul_f32_e32 v4, v36, v0
	v_mul_f32_e32 v0, v20, v0
	v_cvt_pk_bf16_f32 v0, v0, s0
	ds_write_b16 v16, v0 offset:2096
	v_rcp_f32_e32 v0, v1
	v_cvt_pk_bf16_f32 v4, v4, s0
	ds_write_b16 v16, v4 offset:2032
	v_mul_f32_e32 v1, v5, v0
	v_cvt_pk_bf16_f32 v1, v1, s0
	ds_write_b16 v16, v1 offset:2176
	v_mul_f32_e32 v1, v53, v0
	v_cvt_pk_bf16_f32 v1, v1, s0
	ds_write_b16 v16, v1 offset:2240
	v_mul_f32_e32 v1, v37, v0
	v_mul_f32_e32 v0, v21, v0
	v_cvt_pk_bf16_f32 v0, v0, s0
	ds_write_b16 v16, v0 offset:2368
	v_rcp_f32_e32 v0, v2
	v_cvt_pk_bf16_f32 v1, v1, s0
	ds_write_b16 v16, v1 offset:2304
	v_mul_f32_e32 v1, v6, v0
	v_cvt_pk_bf16_f32 v1, v1, s0
	ds_write_b16 v16, v1 offset:2448
	v_mul_f32_e32 v1, v54, v0
	v_cvt_pk_bf16_f32 v1, v1, s0
	ds_write_b16 v16, v1 offset:2512
	v_mul_f32_e32 v1, v38, v0
	v_mul_f32_e32 v0, v22, v0
	v_cvt_pk_bf16_f32 v0, v0, s0
	ds_write_b16 v16, v0 offset:2640
	v_rcp_f32_e32 v0, v3
	v_cvt_pk_bf16_f32 v1, v1, s0
	ds_write_b16 v16, v1 offset:2576
	v_mul_f32_e32 v1, v7, v0
	v_cvt_pk_bf16_f32 v1, v1, s0
	ds_write_b16 v16, v1 offset:2720
	v_mul_f32_e32 v1, v55, v0
	v_cvt_pk_bf16_f32 v1, v1, s0
	ds_write_b16 v16, v1 offset:2784
	v_mul_f32_e32 v1, v39, v0
	v_mul_f32_e32 v0, v23, v0
	v_cvt_pk_bf16_f32 v1, v1, s0
	v_cvt_pk_bf16_f32 v0, v0, s0
	ds_write_b16 v16, v1 offset:2848
	ds_write_b16 v16, v0 offset:2912
	ds_read_b128 v[0:3], v65 offset:64
	s_waitcnt lgkmcnt(0)
	v_rcp_f32_e32 v0, v0
	s_nop 0
	v_mul_f32_e32 v4, v8, v0
	v_cvt_pk_bf16_f32 v4, v4, s0
	ds_write_b16 v16, v4 offset:4080
	v_mul_f32_e32 v4, v56, v0
	v_cvt_pk_bf16_f32 v4, v4, s0
	ds_write_b16 v16, v4 offset:4144
	v_mul_f32_e32 v4, v40, v0
	v_mul_f32_e32 v0, v24, v0
	v_cvt_pk_bf16_f32 v0, v0, s0
	ds_write_b16 v16, v0 offset:4272
	v_rcp_f32_e32 v0, v1
	v_cvt_pk_bf16_f32 v4, v4, s0
	ds_write_b16 v16, v4 offset:4208
	v_mul_f32_e32 v1, v9, v0
	v_cvt_pk_bf16_f32 v1, v1, s0
	ds_write_b16 v16, v1 offset:4352
	v_mul_f32_e32 v1, v57, v0
	v_cvt_pk_bf16_f32 v1, v1, s0
	ds_write_b16 v16, v1 offset:4416
	v_mul_f32_e32 v1, v41, v0
	v_mul_f32_e32 v0, v25, v0
	v_cvt_pk_bf16_f32 v0, v0, s0
	ds_write_b16 v16, v0 offset:4544
	v_rcp_f32_e32 v0, v2
	v_cvt_pk_bf16_f32 v1, v1, s0
	ds_write_b16 v16, v1 offset:4480
	v_mul_f32_e32 v1, v10, v0
	v_cvt_pk_bf16_f32 v1, v1, s0
	ds_write_b16 v16, v1 offset:4624
	v_mul_f32_e32 v1, v58, v0
	v_cvt_pk_bf16_f32 v1, v1, s0
	ds_write_b16 v16, v1 offset:4688
	v_mul_f32_e32 v1, v42, v0
	v_mul_f32_e32 v0, v26, v0
	v_cvt_pk_bf16_f32 v0, v0, s0
	ds_write_b16 v16, v0 offset:4816
	v_rcp_f32_e32 v0, v3
	v_cvt_pk_bf16_f32 v1, v1, s0
	ds_write_b16 v16, v1 offset:4752
	v_mul_f32_e32 v1, v11, v0
	v_cvt_pk_bf16_f32 v1, v1, s0
	ds_write_b16 v16, v1 offset:4896
	v_mul_f32_e32 v1, v59, v0
	v_cvt_pk_bf16_f32 v1, v1, s0
	ds_write_b16 v16, v1 offset:4960
	v_mul_f32_e32 v1, v43, v0
	v_mul_f32_e32 v0, v27, v0
	v_cvt_pk_bf16_f32 v1, v1, s0
	v_cvt_pk_bf16_f32 v0, v0, s0
	ds_write_b16 v16, v1 offset:5024
	ds_write_b16 v16, v0 offset:5088
	ds_read_b128 v[0:3], v65 offset:96
	s_waitcnt lgkmcnt(0)
; __device__ __forceinline__ unsigned cvt_pk_bf16(float lo, float hi) { f32x2_t v = {lo, hi}; bf16x2_t r = __builtin_convertvector(v, bf16x2_t); return __builtin_bit_cast(unsigned, r); }
; __device__ __forceinline__ float bf_lo(unsigned w) { return __uint_as_float(w << 16); }
; __device__ __forceinline__ float bf_hi(unsigned w) { return __uint_as_float(w & 0xffff0000u); }
; __device__ __forceinline__ int crow(int r, int hi) { return (r & 3) + 8 * (r >> 2) + 4 * hi; }
; template <int MODE, int SDEPTH, bool SIMPLE>
; __device__ __forceinline__ void attn_body(const Unit& U, char* lds, const int tid) {
;     ...
;   for (int r = 0; r < 16; ++r) { const float rl = __builtin_amdgcn_rcpf(li_l[crow(r, hi)]); bf16_t* op = ol + crow(r, hi) * OP + r32;
; #pragma unroll
;     for (int d0 = 0; d0 < 4; ++d0) op[d0 * 32] = (bf16_t)(cvt_pk_bf16(o[d0][r] * rl, 0.f) & 0xffffu); }
;   asm volatile("s_waitcnt lgkmcnt(0)" ::: "memory");
;   { const int cc = (lane & 15) * 8, rb = lane >> 4;
;     u32x4 zz[8];
;     if constexpr (MODE != 2) {
; #pragma unroll
;       for (int i = 0; i < 8; ++i) zz[i] = *(const u32x4*)(U.Z + (long)(wid * QBLK + rb + 4 * i) * U.ldz + cc);
;     }
; #pragma unroll
;     for (int i = 0; i < 8; ++i) { const int row = rb + 4 * i; const long orow = wid * QBLK + row;
;       u32x4 v = *(const u32x4*)(ol + row * OP + cc);
;       if constexpr (MODE != 2) { const u32x4 z = zz[i];
; #pragma unroll
;         for (int q = 0; q < 4; ++q) v[q] = cvt_pk_bf16(bf_lo(v[q]) * bf_lo(z[q]), bf_hi(v[q]) * bf_hi(z[q])); }
;       *(u32x4*)(U.O + orow * U.ldo + cc) = v; } }
; __global__ void __launch_bounds__(512) mega(Args a) {
;     ...
;       if (P2MASK & 4) for (int un = cu; un < 3 * NB * 4 * 32; un += G) {
	v_rcp_f32_e32 v0, v0
	s_nop 0
	v_mul_f32_e32 v4, v12, v0
	v_cvt_pk_bf16_f32 v4, v4, s0
	ds_write_b16 v16, v4 offset:6256
	v_mul_f32_e32 v4, v60, v0
	v_cvt_pk_bf16_f32 v4, v4, s0
	ds_write_b16 v16, v4 offset:6320
	v_mul_f32_e32 v4, v44, v0
	v_mul_f32_e32 v0, v28, v0
	v_cvt_pk_bf16_f32 v0, v0, s0
	ds_write_b16 v16, v0 offset:6448
	v_rcp_f32_e32 v0, v1
	v_cvt_pk_bf16_f32 v4, v4, s0
	ds_write_b16 v16, v4 offset:6384
	v_mul_f32_e32 v1, v13, v0
	v_cvt_pk_bf16_f32 v1, v1, s0
	ds_write_b16 v16, v1 offset:6528
	v_mul_f32_e32 v1, v61, v0
	v_cvt_pk_bf16_f32 v1, v1, s0
	ds_write_b16 v16, v1 offset:6592
	v_mul_f32_e32 v1, v45, v0
	v_mul_f32_e32 v0, v29, v0
	v_cvt_pk_bf16_f32 v0, v0, s0
	ds_write_b16 v16, v0 offset:6720
	v_rcp_f32_e32 v0, v2
	v_cvt_pk_bf16_f32 v1, v1, s0
	ds_write_b16 v16, v1 offset:6656
	v_mul_f32_e32 v1, v14, v0
	v_cvt_pk_bf16_f32 v1, v1, s0
	ds_write_b16 v16, v1 offset:6800
	v_mul_f32_e32 v1, v62, v0
	v_cvt_pk_bf16_f32 v1, v1, s0
	ds_write_b16 v16, v1 offset:6864
	v_mul_f32_e32 v1, v46, v0
	v_mul_f32_e32 v0, v30, v0
	v_cvt_pk_bf16_f32 v0, v0, s0
	ds_write_b16 v16, v0 offset:6992
	v_rcp_f32_e32 v0, v3
	v_cvt_pk_bf16_f32 v1, v1, s0
	ds_write_b16 v16, v1 offset:6928
	v_mul_f32_e32 v1, v15, v0
	v_cvt_pk_bf16_f32 v1, v1, s0
	ds_write_b16 v16, v1 offset:7072
	v_mul_f32_e32 v1, v63, v0
	v_cvt_pk_bf16_f32 v1, v1, s0
	ds_write_b16 v16, v1 offset:7136
	v_mul_f32_e32 v1, v47, v0
	v_mul_f32_e32 v0, v31, v0
	v_cvt_pk_bf16_f32 v0, v0, s0
	v_cvt_pk_bf16_f32 v1, v1, s0
	ds_write_b16 v16, v0 offset:7264
	v_lshrrev_b32_e32 v0, 4, v147
	ds_write_b16 v16, v1 offset:7200
	v_or_b32_e32 v4, v0, v154
	v_mul_u32_u24_e32 v0, 0x110, v0
	s_waitcnt lgkmcnt(0)
	v_add3_u32 v8, v64, v192, v0
	ds_read_b128 v[0:3], v8
	v_ashrrev_i32_e32 v5, 31, v4
	v_lshlrev_b64 v[6:7], s2, v[4:5]
	v_lshl_add_u64 v[6:7], v[6:7], 1, s[0:1]
	v_lshl_add_u64 v[6:7], v[6:7], 0, v[192:193]
	s_waitcnt lgkmcnt(0)
	global_store_dwordx4 v[6:7], v[0:3], off sc1
	v_or_b32_e32 v6, 4, v4
	ds_read_b128 v[0:3], v8 offset:1088
	v_ashrrev_i32_e32 v7, 31, v6
	v_lshlrev_b64 v[6:7], s2, v[6:7]
	v_lshl_add_u64 v[6:7], v[6:7], 1, s[0:1]
	v_lshl_add_u64 v[6:7], v[6:7], 0, v[192:193]
	s_waitcnt lgkmcnt(0)
	global_store_dwordx4 v[6:7], v[0:3], off sc1
	v_or_b32_e32 v6, 8, v4
	ds_read_b128 v[0:3], v8 offset:2176
	v_ashrrev_i32_e32 v7, 31, v6
	v_lshlrev_b64 v[6:7], s2, v[6:7]
	v_lshl_add_u64 v[6:7], v[6:7], 1, s[0:1]
	v_lshl_add_u64 v[6:7], v[6:7], 0, v[192:193]
	s_waitcnt lgkmcnt(0)
	global_store_dwordx4 v[6:7], v[0:3], off sc1
	v_or_b32_e32 v6, 12, v4
	ds_read_b128 v[0:3], v8 offset:3264
	v_ashrrev_i32_e32 v7, 31, v6
	v_lshlrev_b64 v[6:7], s2, v[6:7]
	v_lshl_add_u64 v[6:7], v[6:7], 1, s[0:1]
	v_lshl_add_u64 v[6:7], v[6:7], 0, v[192:193]
	s_waitcnt lgkmcnt(0)
	global_store_dwordx4 v[6:7], v[0:3], off sc1
	v_or_b32_e32 v6, 16, v4
	ds_read_b128 v[0:3], v8 offset:4352
	v_ashrrev_i32_e32 v7, 31, v6
	v_lshlrev_b64 v[6:7], s2, v[6:7]
	v_lshl_add_u64 v[6:7], v[6:7], 1, s[0:1]
	v_lshl_add_u64 v[6:7], v[6:7], 0, v[192:193]
	s_waitcnt lgkmcnt(0)
	global_store_dwordx4 v[6:7], v[0:3], off sc1
	v_or_b32_e32 v6, 20, v4
	ds_read_b128 v[0:3], v8 offset:5440
	v_ashrrev_i32_e32 v7, 31, v6
	v_lshlrev_b64 v[6:7], s2, v[6:7]
	v_lshl_add_u64 v[6:7], v[6:7], 1, s[0:1]
	v_lshl_add_u64 v[6:7], v[6:7], 0, v[192:193]
	s_waitcnt lgkmcnt(0)
	global_store_dwordx4 v[6:7], v[0:3], off sc1
	v_or_b32_e32 v6, 24, v4
	ds_read_b128 v[0:3], v8 offset:6528
	v_ashrrev_i32_e32 v7, 31, v6
	v_lshlrev_b64 v[6:7], s2, v[6:7]
	v_lshl_add_u64 v[6:7], v[6:7], 1, s[0:1]
	v_lshl_add_u64 v[6:7], v[6:7], 0, v[192:193]
	v_or_b32_e32 v4, 28, v4
	s_waitcnt lgkmcnt(0)
	global_store_dwordx4 v[6:7], v[0:3], off sc1
	v_ashrrev_i32_e32 v5, 31, v4
	ds_read_b128 v[0:3], v8 offset:7616
	v_lshlrev_b64 v[4:5], s2, v[4:5]
	v_lshl_add_u64 v[4:5], v[4:5], 1, s[0:1]
	v_readlane_b32 s0, v251, 63
	s_add_i32 s22, s22, s0
	v_lshl_add_u64 v[4:5], v[4:5], 0, v[192:193]
	s_cmpk_gt_i32 s22, 0x2ff
	s_waitcnt lgkmcnt(0)
	global_store_dwordx4 v[4:5], v[0:3], off sc1
	s_cbranch_scc1 .LBB0_317
	.p2align	6

; __global__ void __launch_bounds__(512) mega(Args a) {
;     ...
;       for (int m0 = gw; m0 < MT; m0 += 2 * NGW) {
.LBB0_323:
	v_add_u32_e32 v144, s2, v144
	s_movk_i32 s0, 0x3fff
	v_cmp_lt_i32_e32 vcc, s0, v144
	v_lshl_add_u64 v[146:147], v[146:147], 0, s[10:11]
	v_lshl_add_u64 v[148:149], v[148:149], 0, s[10:11]
	v_lshl_add_u64 v[150:151], v[150:151], 0, s[30:31]
	s_or_b64 s[36:37], vcc, s[36:37]
	v_lshl_add_u64 v[152:153], v[152:153], 0, s[30:31]
	s_andn2_b64 exec, exec, s[36:37]
	s_cbranch_execz .LBB0_328
	.p2align	6
